# P3 scan tokens: nop-free order that also keeps one instruction between every VALU result and its first consumer (DPP pairs adjacent, state updates after both final reduction steps)
# speedup vs baseline: 1.0139x; 1.0139x over previous
; #define LAS __attribute__((address_space(3)))
; __device__ __forceinline__ void rwkv_scan_prompt(const Params& p, LAS unsigned char* lds, int bh, int rq) {
;     ...
;             const LAS float* ob = OPS + buf * TC * 6 * 64;
;             f32x4 r4 = *(const LAS f32x4*)(ob + cg_ * 4), d4 = *(const LAS f32x4*)(ob + 64 + cg_ * 4), k4 = *(const LAS f32x4*)(ob + 128 + cg_ * 4),
;                   a4 = *(const LAS f32x4*)(ob + 256 + cg_ * 4), b4 = *(const LAS f32x4*)(ob + 320 + cg_ * 4);
;             float vv = ob[192 + rq * 16 + rloc];
;             f32x4 rp = r4;
; #pragma unroll
;             for (int tk = 0; tk < TC; ++tk) {
;                 f32x4 nr4 = r4, nd4 = d4, nk4 = k4, na4 = a4, nb4 = b4; float nvv = vv;
;                 if (tk < TC - 1) {
;                     const LAS float* o = ob + (tk + 1) * 6 * 64;
;                     nr4 = *(const LAS f32x4*)(o + cg_ * 4); nd4 = *(const LAS f32x4*)(o + 64 + cg_ * 4); nk4 = *(const LAS f32x4*)(o + 128 + cg_ * 4);
;                     na4 = *(const LAS f32x4*)(o + 256 + cg_ * 4); nb4 = *(const LAS f32x4*)(o + 320 + cg_ * 4);
;                     nvv = o[192 + rq * 16 + rloc];
;                 }
;                 __builtin_amdgcn_sched_barrier(0);
;                 typedef float f32x2_ __attribute__((ext_vector_type(2)));
;                 f32x2_ ta = (f32x2_){S[0], S[1]} * (f32x2_){a4[0], a4[1]}; ta = (f32x2_){S[2], S[3]} * (f32x2_){a4[2], a4[3]} + ta;
;                 f32x2_ ty = (f32x2_){S[0], S[1]} * (f32x2_){rp[0], rp[1]}; ty = (f32x2_){S[2], S[3]} * (f32x2_){rp[2], rp[3]} + ty;
;                 const f32x4 T = S * d4 + vv * k4;
;                 float sa = ta[0] + ta[1];
;                 float yp = ty[0] + ty[1];
;                 sa = dpp_add<0xB1>(sa); yp = dpp_add<0xB1>(yp);
;                 sa = dpp_add<0x4E>(sa); yp = dpp_add<0x4E>(yp);
;                 sa = dpp_add<0x124>(sa); yp = dpp_add<0x124>(yp);
;                 sa = dpp_add<0x128>(sa); yp = dpp_add<0x128>(yp);
;                 if (tk > 0) yk[(tk - 1) >> 4] = (cg_ == ((tk - 1) & 15)) ? yp : yk[(tk - 1) >> 4];
;                 S = sa * b4 + T;
;                 rp = r4;
;                 r4 = nr4; d4 = nd4; k4 = nk4; a4 = na4; b4 = nb4; vv = nvv;
.LBB0_336:
	s_and_b32 s95, s73, 1
	s_and_saveexec_b64 s[74:75], s[38:39]
	s_xor_b64 s[74:75], exec, s[74:75]
	s_cbranch_execz .LBB0_338
	s_mul_i32 s78, s95, 0xc000
	s_add_i32 s78, s78, 0
	v_lshl_add_u32 v28, v36, 2, s78
	v_lshl_add_u32 v29, v154, 2, s78
	ds_read_b128 v[30:33], v28
	ds_read_b128 v[160:163], v28 offset:256
	ds_read_b128 v[164:167], v28 offset:512
	ds_read_b128 v[168:171], v28 offset:1024
	ds_read2st64_b32 v[34:35], v29 offset0:3 offset1:9
	ds_read_b128 v[172:175], v28 offset:1280
	ds_read_b128 v[176:179], v28 offset:1536
	ds_read_b128 v[180:183], v28 offset:1792
	ds_read_b128 v[184:187], v28 offset:2048
	ds_read_b128 v[188:191], v28 offset:2560
	ds_read_b128 v[192:195], v28 offset:2816
	s_waitcnt lgkmcnt(7)
	v_pk_mul_f32 v[170:171], v[26:27], v[170:171]
	s_waitcnt lgkmcnt(6)
	v_pk_mul_f32 v[164:165], v[164:165], v[34:35] op_sel_hi:[1,0]
	v_pk_fma_f32 v[168:169], v[24:25], v[168:169], v[170:171]
	v_pk_mul_f32 v[166:167], v[166:167], v[34:35] op_sel_hi:[1,0]
	v_add_f32_e32 v168, v168, v169
	v_pk_fma_f32 v[26:27], v[26:27], v[162:163], v[166:167]
	v_pk_fma_f32 v[24:25], v[24:25], v[160:161], v[164:165]
	v_add_f32_dpp v168, v168, v168 quad_perm:[1,0,3,2] row_mask:0xf bank_mask:0xf bound_ctrl:1
	s_nop 1
	v_add_f32_dpp v168, v168, v168 quad_perm:[2,3,0,1] row_mask:0xf bank_mask:0xf bound_ctrl:1
	s_nop 1
	v_add_f32_dpp v168, v168, v168 row_ror:4 row_mask:0xf bank_mask:0xf bound_ctrl:1
	s_nop 1
	v_add_f32_dpp v168, v168, v168 row_ror:8 row_mask:0xf bank_mask:0xf bound_ctrl:1
	s_waitcnt lgkmcnt(5)
	v_pk_fma_f32 v[196:197], v[172:173], v[168:169], v[24:25] op_sel_hi:[1,0,1]
	v_pk_fma_f32 v[198:199], v[174:175], v[168:169], v[26:27] op_sel_hi:[1,0,1]
	ds_read_b128 v[24:27], v28 offset:3072
	ds_read_b128 v[160:163], v28 offset:3328
	ds_read_b128 v[164:167], v28 offset:3584
	ds_read_b128 v[168:171], v28 offset:4096
	ds_read_b128 v[172:175], v28 offset:4352
	ds_read_b32 v34, v29 offset:3840
	s_waitcnt lgkmcnt(7)
	v_pk_mul_f32 v[190:191], v[190:191], v[198:199]
	v_pk_mul_f32 v[32:33], v[32:33], v[198:199]
	v_pk_fma_f32 v[188:189], v[188:189], v[196:197], v[190:191]
	v_pk_fma_f32 v[30:31], v[30:31], v[196:197], v[32:33]
	v_pk_mul_f32 v[32:33], v[180:181], v[196:197]
	v_add_f32_e32 v206, v188, v189
	v_add_f32_e32 v30, v30, v31
	v_pk_mul_f32 v[180:181], v[182:183], v[198:199]
	v_add_f32_dpp v31, v206, v206 quad_perm:[1,0,3,2] row_mask:0xf bank_mask:0xf bound_ctrl:1
	v_add_f32_dpp v30, v30, v30 quad_perm:[1,0,3,2] row_mask:0xf bank_mask:0xf bound_ctrl:1
	v_mov_b32_e32 v182, v35
	v_add_f32_dpp v31, v31, v31 quad_perm:[2,3,0,1] row_mask:0xf bank_mask:0xf bound_ctrl:1
	v_add_f32_dpp v30, v30, v30 quad_perm:[2,3,0,1] row_mask:0xf bank_mask:0xf bound_ctrl:1
	v_pk_fma_f32 v[180:181], v[186:187], v[182:183], v[180:181] op_sel_hi:[1,0,1]
	v_add_f32_dpp v31, v31, v31 row_ror:4 row_mask:0xf bank_mask:0xf bound_ctrl:1
	v_add_f32_dpp v35, v30, v30 row_ror:4 row_mask:0xf bank_mask:0xf bound_ctrl:1
	v_pk_fma_f32 v[32:33], v[184:185], v[182:183], v[32:33] op_sel_hi:[1,0,1]
	v_add_f32_dpp v30, v31, v31 row_ror:8 row_mask:0xf bank_mask:0xf bound_ctrl:1
	v_add_f32_dpp v31, v35, v35 row_ror:8 row_mask:0xf bank_mask:0xf bound_ctrl:1
	s_waitcnt lgkmcnt(6)
	v_pk_fma_f32 v[196:197], v[192:193], v[30:31], v[32:33] op_sel_hi:[1,0,1]
	v_cndmask_b32_e64 v201, 0, v31, s[6:7]
	v_pk_fma_f32 v[198:199], v[194:195], v[30:31], v[180:181] op_sel_hi:[1,0,1]
	ds_read_b128 v[30:33], v28 offset:4608
	ds_read_b128 v[180:183], v28 offset:4864
	ds_read_b128 v[184:187], v28 offset:5120
	ds_read_b128 v[188:191], v28 offset:5632
	ds_read_b128 v[192:195], v28 offset:5888
	ds_read_b32 v200, v29 offset:5376
	s_waitcnt lgkmcnt(8)
	v_pk_mul_f32 v[170:171], v[170:171], v[198:199]
	v_pk_mul_f32 v[160:161], v[160:161], v[196:197]
	v_pk_fma_f32 v[168:169], v[168:169], v[196:197], v[170:171]
	v_pk_mul_f32 v[170:171], v[178:179], v[198:199]
	v_pk_mul_f32 v[162:163], v[162:163], v[198:199]
	v_pk_fma_f32 v[170:171], v[176:177], v[196:197], v[170:171]
	s_waitcnt lgkmcnt(6)
	v_pk_fma_f32 v[162:163], v[166:167], v[34:35], v[162:163] op_sel_hi:[1,0,1]
	v_add_f32_e32 v206, v168, v169
	v_pk_fma_f32 v[34:35], v[164:165], v[34:35], v[160:161] op_sel_hi:[1,0,1]
	v_add_f32_e32 v161, v170, v171
	v_add_f32_dpp v160, v206, v206 quad_perm:[1,0,3,2] row_mask:0xf bank_mask:0xf bound_ctrl:1
	s_nop 0
	v_add_f32_dpp v161, v161, v161 quad_perm:[1,0,3,2] row_mask:0xf bank_mask:0xf bound_ctrl:1
	v_add_f32_dpp v160, v160, v160 quad_perm:[2,3,0,1] row_mask:0xf bank_mask:0xf bound_ctrl:1
	s_nop 0
	v_add_f32_dpp v161, v161, v161 quad_perm:[2,3,0,1] row_mask:0xf bank_mask:0xf bound_ctrl:1
	v_add_f32_dpp v160, v160, v160 row_ror:4 row_mask:0xf bank_mask:0xf bound_ctrl:1
	s_nop 0
	v_add_f32_dpp v161, v161, v161 row_ror:4 row_mask:0xf bank_mask:0xf bound_ctrl:1
	v_add_f32_dpp v160, v160, v160 row_ror:8 row_mask:0xf bank_mask:0xf bound_ctrl:1
	v_pk_fma_f32 v[34:35], v[172:173], v[160:161], v[34:35] op_sel_hi:[1,0,1]
	v_add_f32_dpp v161, v161, v161 row_ror:8 row_mask:0xf bank_mask:0xf bound_ctrl:1
	v_cndmask_b32_e64 v199, v201, v161, s[8:9]
	v_pk_fma_f32 v[196:197], v[174:175], v[160:161], v[162:163] op_sel_hi:[1,0,1]
	ds_read_b128 v[160:163], v28 offset:6144
	ds_read_b128 v[164:167], v28 offset:6400
	ds_read_b128 v[168:171], v28 offset:6656
	ds_read_b128 v[172:175], v28 offset:7168
	ds_read_b128 v[176:179], v28 offset:7424
	ds_read_b32 v198, v29 offset:6912
	s_waitcnt lgkmcnt(8)
; #define LAS __attribute__((address_space(3)))
; __device__ __forceinline__ void rwkv_scan_prompt(const Params& p, LAS unsigned char* lds, int bh, int rq) {
;     ...
;             for (int tk = 0; tk < TC; ++tk) {
;                 f32x4 nr4 = r4, nd4 = d4, nk4 = k4, na4 = a4, nb4 = b4; float nvv = vv;
;                 if (tk < TC - 1) {
;                     const LAS float* o = ob + (tk + 1) * 6 * 64;
;                     nr4 = *(const LAS f32x4*)(o + cg_ * 4); nd4 = *(const LAS f32x4*)(o + 64 + cg_ * 4); nk4 = *(const LAS f32x4*)(o + 128 + cg_ * 4);
;                     na4 = *(const LAS f32x4*)(o + 256 + cg_ * 4); nb4 = *(const LAS f32x4*)(o + 320 + cg_ * 4);
;                     nvv = o[192 + rq * 16 + rloc];
;                 }
;                 __builtin_amdgcn_sched_barrier(0);
;                 typedef float f32x2_ __attribute__((ext_vector_type(2)));
;                 f32x2_ ta = (f32x2_){S[0], S[1]} * (f32x2_){a4[0], a4[1]}; ta = (f32x2_){S[2], S[3]} * (f32x2_){a4[2], a4[3]} + ta;
;                 f32x2_ ty = (f32x2_){S[0], S[1]} * (f32x2_){rp[0], rp[1]}; ty = (f32x2_){S[2], S[3]} * (f32x2_){rp[2], rp[3]} + ty;
;                 const f32x4 T = S * d4 + vv * k4;
;                 float sa = ta[0] + ta[1];
;                 float yp = ty[0] + ty[1];
;                 sa = dpp_add<0xB1>(sa); yp = dpp_add<0xB1>(yp);
;                 sa = dpp_add<0x4E>(sa); yp = dpp_add<0x4E>(yp);
;                 sa = dpp_add<0x124>(sa); yp = dpp_add<0x124>(yp);
;                 sa = dpp_add<0x128>(sa); yp = dpp_add<0x128>(yp);
;                 if (tk > 0) yk[(tk - 1) >> 4] = (cg_ == ((tk - 1) & 15)) ? yp : yk[(tk - 1) >> 4];
;                 S = sa * b4 + T;
;                 rp = r4;
;                 r4 = nr4; d4 = nd4; k4 = nk4; a4 = na4; b4 = nb4; vv = nvv;
	v_pk_mul_f32 v[190:191], v[190:191], v[196:197]
	v_pk_mul_f32 v[26:27], v[26:27], v[196:197]
	v_pk_fma_f32 v[188:189], v[188:189], v[34:35], v[190:191]
	v_pk_fma_f32 v[24:25], v[24:25], v[34:35], v[26:27]
	v_add_f32_e32 v206, v188, v189
	v_add_f32_e32 v24, v24, v25
	v_pk_mul_f32 v[26:27], v[180:181], v[34:35]
	v_add_f32_dpp v25, v206, v206 quad_perm:[1,0,3,2] row_mask:0xf bank_mask:0xf bound_ctrl:1
	v_add_f32_dpp v24, v24, v24 quad_perm:[1,0,3,2] row_mask:0xf bank_mask:0xf bound_ctrl:1
	v_pk_mul_f32 v[34:35], v[182:183], v[196:197]
	s_waitcnt lgkmcnt(6)
	v_add_f32_dpp v25, v25, v25 quad_perm:[2,3,0,1] row_mask:0xf bank_mask:0xf bound_ctrl:1
	v_add_f32_dpp v24, v24, v24 quad_perm:[2,3,0,1] row_mask:0xf bank_mask:0xf bound_ctrl:1
	v_pk_fma_f32 v[34:35], v[186:187], v[200:201], v[34:35] op_sel_hi:[1,0,1]
	v_add_f32_dpp v25, v25, v25 row_ror:4 row_mask:0xf bank_mask:0xf bound_ctrl:1
	v_add_f32_dpp v180, v24, v24 row_ror:4 row_mask:0xf bank_mask:0xf bound_ctrl:1
	v_pk_fma_f32 v[26:27], v[184:185], v[200:201], v[26:27] op_sel_hi:[1,0,1]
	v_add_f32_dpp v24, v25, v25 row_ror:8 row_mask:0xf bank_mask:0xf bound_ctrl:1
	v_add_f32_dpp v25, v180, v180 row_ror:8 row_mask:0xf bank_mask:0xf bound_ctrl:1
	v_pk_fma_f32 v[196:197], v[192:193], v[24:25], v[26:27] op_sel_hi:[1,0,1]
	v_cndmask_b32_e64 v199, v199, v25, s[10:11]
	v_pk_fma_f32 v[34:35], v[194:195], v[24:25], v[34:35] op_sel_hi:[1,0,1]
	ds_read_b128 v[24:27], v28 offset:7680
	ds_read_b128 v[180:183], v28 offset:7936
	ds_read_b128 v[184:187], v28 offset:8192
	ds_read_b128 v[188:191], v28 offset:8704
	ds_read_b128 v[192:195], v28 offset:8960
	ds_read_b32 v200, v29 offset:8448
	s_waitcnt lgkmcnt(8)
	v_pk_mul_f32 v[174:175], v[174:175], v[34:35]
	v_pk_mul_f32 v[32:33], v[32:33], v[34:35]
	v_pk_fma_f32 v[172:173], v[172:173], v[196:197], v[174:175]
	v_pk_fma_f32 v[30:31], v[30:31], v[196:197], v[32:33]
	v_add_f32_e32 v206, v172, v173
	v_add_f32_e32 v30, v30, v31
	v_pk_mul_f32 v[32:33], v[164:165], v[196:197]
	v_add_f32_dpp v31, v206, v206 quad_perm:[1,0,3,2] row_mask:0xf bank_mask:0xf bound_ctrl:1
	v_add_f32_dpp v30, v30, v30 quad_perm:[1,0,3,2] row_mask:0xf bank_mask:0xf bound_ctrl:1
	v_pk_mul_f32 v[34:35], v[166:167], v[34:35]
	s_waitcnt lgkmcnt(6)
	v_add_f32_dpp v31, v31, v31 quad_perm:[2,3,0,1] row_mask:0xf bank_mask:0xf bound_ctrl:1
	v_add_f32_dpp v30, v30, v30 quad_perm:[2,3,0,1] row_mask:0xf bank_mask:0xf bound_ctrl:1
	v_pk_fma_f32 v[34:35], v[170:171], v[198:199], v[34:35] op_sel_hi:[1,0,1]
	v_add_f32_dpp v31, v31, v31 row_ror:4 row_mask:0xf bank_mask:0xf bound_ctrl:1
	v_add_f32_dpp v164, v30, v30 row_ror:4 row_mask:0xf bank_mask:0xf bound_ctrl:1
	v_pk_fma_f32 v[32:33], v[168:169], v[198:199], v[32:33] op_sel_hi:[1,0,1]
	v_add_f32_dpp v30, v31, v31 row_ror:8 row_mask:0xf bank_mask:0xf bound_ctrl:1
	v_add_f32_dpp v31, v164, v164 row_ror:8 row_mask:0xf bank_mask:0xf bound_ctrl:1
	v_pk_fma_f32 v[196:197], v[176:177], v[30:31], v[32:33] op_sel_hi:[1,0,1]
	v_cndmask_b32_e64 v199, v199, v31, s[12:13]
	v_pk_fma_f32 v[34:35], v[178:179], v[30:31], v[34:35] op_sel_hi:[1,0,1]
	ds_read_b128 v[30:33], v28 offset:9216
	ds_read_b128 v[164:167], v28 offset:9472
	ds_read_b128 v[168:171], v28 offset:9728
	ds_read_b128 v[172:175], v28 offset:10240
	ds_read_b128 v[176:179], v28 offset:10496
	ds_read_b32 v198, v29 offset:9984
	s_waitcnt lgkmcnt(8)
	v_pk_mul_f32 v[190:191], v[190:191], v[34:35]
	v_pk_mul_f32 v[162:163], v[162:163], v[34:35]
	v_pk_fma_f32 v[188:189], v[188:189], v[196:197], v[190:191]
	v_pk_fma_f32 v[160:161], v[160:161], v[196:197], v[162:163]
	v_add_f32_e32 v206, v188, v189
	v_add_f32_e32 v160, v160, v161
	v_pk_mul_f32 v[162:163], v[180:181], v[196:197]
	v_add_f32_dpp v161, v206, v206 quad_perm:[1,0,3,2] row_mask:0xf bank_mask:0xf bound_ctrl:1
	v_add_f32_dpp v160, v160, v160 quad_perm:[1,0,3,2] row_mask:0xf bank_mask:0xf bound_ctrl:1
	v_pk_mul_f32 v[34:35], v[182:183], v[34:35]
	s_waitcnt lgkmcnt(6)
	v_add_f32_dpp v161, v161, v161 quad_perm:[2,3,0,1] row_mask:0xf bank_mask:0xf bound_ctrl:1
	v_add_f32_dpp v160, v160, v160 quad_perm:[2,3,0,1] row_mask:0xf bank_mask:0xf bound_ctrl:1
	v_pk_fma_f32 v[34:35], v[186:187], v[200:201], v[34:35] op_sel_hi:[1,0,1]
	v_add_f32_dpp v161, v161, v161 row_ror:4 row_mask:0xf bank_mask:0xf bound_ctrl:1
	v_add_f32_dpp v180, v160, v160 row_ror:4 row_mask:0xf bank_mask:0xf bound_ctrl:1
	v_pk_fma_f32 v[162:163], v[184:185], v[200:201], v[162:163] op_sel_hi:[1,0,1]
	v_add_f32_dpp v160, v161, v161 row_ror:8 row_mask:0xf bank_mask:0xf bound_ctrl:1
	v_add_f32_dpp v161, v180, v180 row_ror:8 row_mask:0xf bank_mask:0xf bound_ctrl:1
	v_pk_fma_f32 v[196:197], v[192:193], v[160:161], v[162:163] op_sel_hi:[1,0,1]
	v_cndmask_b32_e64 v199, v199, v161, s[14:15]
	v_pk_fma_f32 v[34:35], v[194:195], v[160:161], v[34:35] op_sel_hi:[1,0,1]
	ds_read_b128 v[160:163], v28 offset:10752
	ds_read_b128 v[180:183], v28 offset:11008
	ds_read_b128 v[184:187], v28 offset:11264
	ds_read_b128 v[188:191], v28 offset:11776
	ds_read_b128 v[192:195], v28 offset:12032
	ds_read_b32 v200, v29 offset:11520
	s_waitcnt lgkmcnt(8)
	v_pk_mul_f32 v[174:175], v[174:175], v[34:35]
	v_pk_mul_f32 v[26:27], v[26:27], v[34:35]
	v_pk_fma_f32 v[172:173], v[172:173], v[196:197], v[174:175]
	v_pk_fma_f32 v[24:25], v[24:25], v[196:197], v[26:27]
	v_add_f32_e32 v206, v172, v173
	v_add_f32_e32 v24, v24, v25
	v_pk_mul_f32 v[26:27], v[164:165], v[196:197]
	v_add_f32_dpp v25, v206, v206 quad_perm:[1,0,3,2] row_mask:0xf bank_mask:0xf bound_ctrl:1
	v_add_f32_dpp v24, v24, v24 quad_perm:[1,0,3,2] row_mask:0xf bank_mask:0xf bound_ctrl:1
	v_pk_mul_f32 v[34:35], v[166:167], v[34:35]
	s_waitcnt lgkmcnt(6)
; #define LAS __attribute__((address_space(3)))
; __device__ __forceinline__ void rwkv_scan_prompt(const Params& p, LAS unsigned char* lds, int bh, int rq) {
;     ...
;             for (int tk = 0; tk < TC; ++tk) {
;                 f32x4 nr4 = r4, nd4 = d4, nk4 = k4, na4 = a4, nb4 = b4; float nvv = vv;
;                 if (tk < TC - 1) {
;                     const LAS float* o = ob + (tk + 1) * 6 * 64;
;                     nr4 = *(const LAS f32x4*)(o + cg_ * 4); nd4 = *(const LAS f32x4*)(o + 64 + cg_ * 4); nk4 = *(const LAS f32x4*)(o + 128 + cg_ * 4);
;                     na4 = *(const LAS f32x4*)(o + 256 + cg_ * 4); nb4 = *(const LAS f32x4*)(o + 320 + cg_ * 4);
;                     nvv = o[192 + rq * 16 + rloc];
;                 }
;                 __builtin_amdgcn_sched_barrier(0);
;                 typedef float f32x2_ __attribute__((ext_vector_type(2)));
;                 f32x2_ ta = (f32x2_){S[0], S[1]} * (f32x2_){a4[0], a4[1]}; ta = (f32x2_){S[2], S[3]} * (f32x2_){a4[2], a4[3]} + ta;
;                 f32x2_ ty = (f32x2_){S[0], S[1]} * (f32x2_){rp[0], rp[1]}; ty = (f32x2_){S[2], S[3]} * (f32x2_){rp[2], rp[3]} + ty;
;                 const f32x4 T = S * d4 + vv * k4;
;                 float sa = ta[0] + ta[1];
;                 float yp = ty[0] + ty[1];
;                 sa = dpp_add<0xB1>(sa); yp = dpp_add<0xB1>(yp);
;                 sa = dpp_add<0x4E>(sa); yp = dpp_add<0x4E>(yp);
;                 sa = dpp_add<0x124>(sa); yp = dpp_add<0x124>(yp);
;                 sa = dpp_add<0x128>(sa); yp = dpp_add<0x128>(yp);
;                 if (tk > 0) yk[(tk - 1) >> 4] = (cg_ == ((tk - 1) & 15)) ? yp : yk[(tk - 1) >> 4];
;                 S = sa * b4 + T;
;                 rp = r4;
;                 r4 = nr4; d4 = nd4; k4 = nk4; a4 = na4; b4 = nb4; vv = nvv;
	v_add_f32_dpp v25, v25, v25 quad_perm:[2,3,0,1] row_mask:0xf bank_mask:0xf bound_ctrl:1
	v_add_f32_dpp v24, v24, v24 quad_perm:[2,3,0,1] row_mask:0xf bank_mask:0xf bound_ctrl:1
	v_pk_fma_f32 v[34:35], v[170:171], v[198:199], v[34:35] op_sel_hi:[1,0,1]
	v_add_f32_dpp v25, v25, v25 row_ror:4 row_mask:0xf bank_mask:0xf bound_ctrl:1
	v_add_f32_dpp v164, v24, v24 row_ror:4 row_mask:0xf bank_mask:0xf bound_ctrl:1
	v_pk_fma_f32 v[26:27], v[168:169], v[198:199], v[26:27] op_sel_hi:[1,0,1]
	v_add_f32_dpp v24, v25, v25 row_ror:8 row_mask:0xf bank_mask:0xf bound_ctrl:1
	v_add_f32_dpp v25, v164, v164 row_ror:8 row_mask:0xf bank_mask:0xf bound_ctrl:1
	v_pk_fma_f32 v[196:197], v[176:177], v[24:25], v[26:27] op_sel_hi:[1,0,1]
	v_cndmask_b32_e64 v199, v199, v25, s[16:17]
	v_pk_fma_f32 v[34:35], v[178:179], v[24:25], v[34:35] op_sel_hi:[1,0,1]
	ds_read_b128 v[24:27], v28 offset:12288
	ds_read_b128 v[164:167], v28 offset:12544
	ds_read_b128 v[168:171], v28 offset:12800
	ds_read_b128 v[172:175], v28 offset:13312
	ds_read_b128 v[176:179], v28 offset:13568
	ds_read_b32 v198, v29 offset:13056
	s_waitcnt lgkmcnt(8)
	v_pk_mul_f32 v[190:191], v[190:191], v[34:35]
	v_pk_mul_f32 v[32:33], v[32:33], v[34:35]
	v_pk_fma_f32 v[188:189], v[188:189], v[196:197], v[190:191]
	v_pk_fma_f32 v[30:31], v[30:31], v[196:197], v[32:33]
	v_add_f32_e32 v206, v188, v189
	v_add_f32_e32 v30, v30, v31
	v_pk_mul_f32 v[32:33], v[180:181], v[196:197]
	v_add_f32_dpp v31, v206, v206 quad_perm:[1,0,3,2] row_mask:0xf bank_mask:0xf bound_ctrl:1
	v_add_f32_dpp v30, v30, v30 quad_perm:[1,0,3,2] row_mask:0xf bank_mask:0xf bound_ctrl:1
	v_pk_mul_f32 v[34:35], v[182:183], v[34:35]
	s_waitcnt lgkmcnt(6)
	v_add_f32_dpp v31, v31, v31 quad_perm:[2,3,0,1] row_mask:0xf bank_mask:0xf bound_ctrl:1
	v_add_f32_dpp v30, v30, v30 quad_perm:[2,3,0,1] row_mask:0xf bank_mask:0xf bound_ctrl:1
	v_pk_fma_f32 v[34:35], v[186:187], v[200:201], v[34:35] op_sel_hi:[1,0,1]
	v_add_f32_dpp v31, v31, v31 row_ror:4 row_mask:0xf bank_mask:0xf bound_ctrl:1
	v_add_f32_dpp v180, v30, v30 row_ror:4 row_mask:0xf bank_mask:0xf bound_ctrl:1
	v_pk_fma_f32 v[32:33], v[184:185], v[200:201], v[32:33] op_sel_hi:[1,0,1]
	v_add_f32_dpp v30, v31, v31 row_ror:8 row_mask:0xf bank_mask:0xf bound_ctrl:1
	v_add_f32_dpp v31, v180, v180 row_ror:8 row_mask:0xf bank_mask:0xf bound_ctrl:1
	v_pk_fma_f32 v[196:197], v[192:193], v[30:31], v[32:33] op_sel_hi:[1,0,1]
	v_cndmask_b32_e64 v199, v199, v31, s[18:19]
	v_pk_fma_f32 v[34:35], v[194:195], v[30:31], v[34:35] op_sel_hi:[1,0,1]
	ds_read_b128 v[30:33], v28 offset:13824
	ds_read_b128 v[180:183], v28 offset:14080
	ds_read_b128 v[184:187], v28 offset:14336
	ds_read_b128 v[188:191], v28 offset:14848
	ds_read_b128 v[192:195], v28 offset:15104
	ds_read_b32 v200, v29 offset:14592
	s_waitcnt lgkmcnt(8)
	v_pk_mul_f32 v[174:175], v[174:175], v[34:35]
	v_pk_mul_f32 v[162:163], v[162:163], v[34:35]
	v_pk_fma_f32 v[172:173], v[172:173], v[196:197], v[174:175]
	v_pk_fma_f32 v[160:161], v[160:161], v[196:197], v[162:163]
	v_add_f32_e32 v206, v172, v173
	v_add_f32_e32 v160, v160, v161
	v_pk_mul_f32 v[162:163], v[164:165], v[196:197]
	v_add_f32_dpp v161, v206, v206 quad_perm:[1,0,3,2] row_mask:0xf bank_mask:0xf bound_ctrl:1
	v_add_f32_dpp v160, v160, v160 quad_perm:[1,0,3,2] row_mask:0xf bank_mask:0xf bound_ctrl:1
	v_pk_mul_f32 v[34:35], v[166:167], v[34:35]
	s_waitcnt lgkmcnt(6)
	v_add_f32_dpp v161, v161, v161 quad_perm:[2,3,0,1] row_mask:0xf bank_mask:0xf bound_ctrl:1
	v_add_f32_dpp v160, v160, v160 quad_perm:[2,3,0,1] row_mask:0xf bank_mask:0xf bound_ctrl:1
	v_pk_fma_f32 v[34:35], v[170:171], v[198:199], v[34:35] op_sel_hi:[1,0,1]
	v_add_f32_dpp v161, v161, v161 row_ror:4 row_mask:0xf bank_mask:0xf bound_ctrl:1
	v_add_f32_dpp v164, v160, v160 row_ror:4 row_mask:0xf bank_mask:0xf bound_ctrl:1
	v_pk_fma_f32 v[162:163], v[168:169], v[198:199], v[162:163] op_sel_hi:[1,0,1]
	v_add_f32_dpp v160, v161, v161 row_ror:8 row_mask:0xf bank_mask:0xf bound_ctrl:1
	v_add_f32_dpp v161, v164, v164 row_ror:8 row_mask:0xf bank_mask:0xf bound_ctrl:1
	v_pk_fma_f32 v[196:197], v[176:177], v[160:161], v[162:163] op_sel_hi:[1,0,1]
	v_cndmask_b32_e64 v199, v199, v161, s[20:21]
	v_pk_fma_f32 v[34:35], v[178:179], v[160:161], v[34:35] op_sel_hi:[1,0,1]
	ds_read_b128 v[160:163], v28 offset:15360
	ds_read_b128 v[164:167], v28 offset:15616
	ds_read_b128 v[168:171], v28 offset:15872
	ds_read_b128 v[172:175], v28 offset:16384
	ds_read_b128 v[176:179], v28 offset:16640
	ds_read_b32 v198, v29 offset:16128
	s_waitcnt lgkmcnt(8)
	v_pk_mul_f32 v[190:191], v[190:191], v[34:35]
	v_pk_mul_f32 v[26:27], v[26:27], v[34:35]
	v_pk_fma_f32 v[188:189], v[188:189], v[196:197], v[190:191]
	v_pk_fma_f32 v[24:25], v[24:25], v[196:197], v[26:27]
	v_add_f32_e32 v206, v188, v189
	v_add_f32_e32 v24, v24, v25
	v_pk_mul_f32 v[26:27], v[180:181], v[196:197]
	v_add_f32_dpp v25, v206, v206 quad_perm:[1,0,3,2] row_mask:0xf bank_mask:0xf bound_ctrl:1
	v_add_f32_dpp v24, v24, v24 quad_perm:[1,0,3,2] row_mask:0xf bank_mask:0xf bound_ctrl:1
	v_pk_mul_f32 v[34:35], v[182:183], v[34:35]
	s_waitcnt lgkmcnt(6)
	v_add_f32_dpp v25, v25, v25 quad_perm:[2,3,0,1] row_mask:0xf bank_mask:0xf bound_ctrl:1
	v_add_f32_dpp v24, v24, v24 quad_perm:[2,3,0,1] row_mask:0xf bank_mask:0xf bound_ctrl:1
	v_pk_fma_f32 v[34:35], v[186:187], v[200:201], v[34:35] op_sel_hi:[1,0,1]
	v_add_f32_dpp v25, v25, v25 row_ror:4 row_mask:0xf bank_mask:0xf bound_ctrl:1
	v_add_f32_dpp v180, v24, v24 row_ror:4 row_mask:0xf bank_mask:0xf bound_ctrl:1
	v_pk_fma_f32 v[26:27], v[184:185], v[200:201], v[26:27] op_sel_hi:[1,0,1]
	v_add_f32_dpp v24, v25, v25 row_ror:8 row_mask:0xf bank_mask:0xf bound_ctrl:1
	v_add_f32_dpp v25, v180, v180 row_ror:8 row_mask:0xf bank_mask:0xf bound_ctrl:1
	v_pk_fma_f32 v[196:197], v[192:193], v[24:25], v[26:27] op_sel_hi:[1,0,1]
	v_cndmask_b32_e64 v199, v199, v25, s[22:23]
	v_pk_fma_f32 v[34:35], v[194:195], v[24:25], v[34:35] op_sel_hi:[1,0,1]
	ds_read_b128 v[24:27], v28 offset:16896
	ds_read_b128 v[180:183], v28 offset:17152
	ds_read_b128 v[184:187], v28 offset:17408
	ds_read_b128 v[188:191], v28 offset:17920
	ds_read_b128 v[192:195], v28 offset:18176
	ds_read_b32 v200, v29 offset:17664
	s_waitcnt lgkmcnt(8)
; #define LAS __attribute__((address_space(3)))
; __device__ __forceinline__ void rwkv_scan_prompt(const Params& p, LAS unsigned char* lds, int bh, int rq) {
;     ...
;             for (int tk = 0; tk < TC; ++tk) {
;                 f32x4 nr4 = r4, nd4 = d4, nk4 = k4, na4 = a4, nb4 = b4; float nvv = vv;
;                 if (tk < TC - 1) {
;                     const LAS float* o = ob + (tk + 1) * 6 * 64;
;                     nr4 = *(const LAS f32x4*)(o + cg_ * 4); nd4 = *(const LAS f32x4*)(o + 64 + cg_ * 4); nk4 = *(const LAS f32x4*)(o + 128 + cg_ * 4);
;                     na4 = *(const LAS f32x4*)(o + 256 + cg_ * 4); nb4 = *(const LAS f32x4*)(o + 320 + cg_ * 4);
;                     nvv = o[192 + rq * 16 + rloc];
;                 }
;                 __builtin_amdgcn_sched_barrier(0);
;                 typedef float f32x2_ __attribute__((ext_vector_type(2)));
;                 f32x2_ ta = (f32x2_){S[0], S[1]} * (f32x2_){a4[0], a4[1]}; ta = (f32x2_){S[2], S[3]} * (f32x2_){a4[2], a4[3]} + ta;
;                 f32x2_ ty = (f32x2_){S[0], S[1]} * (f32x2_){rp[0], rp[1]}; ty = (f32x2_){S[2], S[3]} * (f32x2_){rp[2], rp[3]} + ty;
;                 const f32x4 T = S * d4 + vv * k4;
;                 float sa = ta[0] + ta[1];
;                 float yp = ty[0] + ty[1];
;                 sa = dpp_add<0xB1>(sa); yp = dpp_add<0xB1>(yp);
;                 sa = dpp_add<0x4E>(sa); yp = dpp_add<0x4E>(yp);
;                 sa = dpp_add<0x124>(sa); yp = dpp_add<0x124>(yp);
;                 sa = dpp_add<0x128>(sa); yp = dpp_add<0x128>(yp);
;                 if (tk > 0) yk[(tk - 1) >> 4] = (cg_ == ((tk - 1) & 15)) ? yp : yk[(tk - 1) >> 4];
;                 S = sa * b4 + T;
;                 rp = r4;
;                 r4 = nr4; d4 = nd4; k4 = nk4; a4 = na4; b4 = nb4; vv = nvv;
	v_pk_mul_f32 v[174:175], v[174:175], v[34:35]
	v_pk_mul_f32 v[32:33], v[32:33], v[34:35]
	v_pk_fma_f32 v[172:173], v[172:173], v[196:197], v[174:175]
	v_pk_fma_f32 v[30:31], v[30:31], v[196:197], v[32:33]
	v_add_f32_e32 v206, v172, v173
	v_add_f32_e32 v30, v30, v31
	v_pk_mul_f32 v[32:33], v[164:165], v[196:197]
	v_add_f32_dpp v31, v206, v206 quad_perm:[1,0,3,2] row_mask:0xf bank_mask:0xf bound_ctrl:1
	v_add_f32_dpp v30, v30, v30 quad_perm:[1,0,3,2] row_mask:0xf bank_mask:0xf bound_ctrl:1
	v_pk_mul_f32 v[34:35], v[166:167], v[34:35]
	s_waitcnt lgkmcnt(6)
	v_add_f32_dpp v31, v31, v31 quad_perm:[2,3,0,1] row_mask:0xf bank_mask:0xf bound_ctrl:1
	v_add_f32_dpp v30, v30, v30 quad_perm:[2,3,0,1] row_mask:0xf bank_mask:0xf bound_ctrl:1
	v_pk_fma_f32 v[34:35], v[170:171], v[198:199], v[34:35] op_sel_hi:[1,0,1]
	v_add_f32_dpp v31, v31, v31 row_ror:4 row_mask:0xf bank_mask:0xf bound_ctrl:1
	v_add_f32_dpp v164, v30, v30 row_ror:4 row_mask:0xf bank_mask:0xf bound_ctrl:1
	v_pk_fma_f32 v[32:33], v[168:169], v[198:199], v[32:33] op_sel_hi:[1,0,1]
	v_add_f32_dpp v30, v31, v31 row_ror:8 row_mask:0xf bank_mask:0xf bound_ctrl:1
	v_add_f32_dpp v31, v164, v164 row_ror:8 row_mask:0xf bank_mask:0xf bound_ctrl:1
	v_pk_fma_f32 v[196:197], v[176:177], v[30:31], v[32:33] op_sel_hi:[1,0,1]
	v_cndmask_b32_e64 v199, v199, v31, s[24:25]
	v_pk_fma_f32 v[34:35], v[178:179], v[30:31], v[34:35] op_sel_hi:[1,0,1]
	ds_read_b128 v[30:33], v28 offset:18432
	ds_read_b128 v[164:167], v28 offset:18688
	ds_read_b128 v[168:171], v28 offset:18944
	ds_read_b128 v[172:175], v28 offset:19456
	ds_read_b128 v[176:179], v28 offset:19712
	ds_read_b32 v198, v29 offset:19200
	s_waitcnt lgkmcnt(8)
	v_pk_mul_f32 v[190:191], v[190:191], v[34:35]
	v_pk_mul_f32 v[162:163], v[162:163], v[34:35]
	v_pk_fma_f32 v[188:189], v[188:189], v[196:197], v[190:191]
	v_pk_fma_f32 v[160:161], v[160:161], v[196:197], v[162:163]
	v_add_f32_e32 v206, v188, v189
	v_add_f32_e32 v160, v160, v161
	v_pk_mul_f32 v[162:163], v[180:181], v[196:197]
	v_add_f32_dpp v161, v206, v206 quad_perm:[1,0,3,2] row_mask:0xf bank_mask:0xf bound_ctrl:1
	v_add_f32_dpp v160, v160, v160 quad_perm:[1,0,3,2] row_mask:0xf bank_mask:0xf bound_ctrl:1
	v_pk_mul_f32 v[34:35], v[182:183], v[34:35]
	s_waitcnt lgkmcnt(6)
	v_add_f32_dpp v161, v161, v161 quad_perm:[2,3,0,1] row_mask:0xf bank_mask:0xf bound_ctrl:1
	v_add_f32_dpp v160, v160, v160 quad_perm:[2,3,0,1] row_mask:0xf bank_mask:0xf bound_ctrl:1
	v_pk_fma_f32 v[34:35], v[186:187], v[200:201], v[34:35] op_sel_hi:[1,0,1]
	v_add_f32_dpp v161, v161, v161 row_ror:4 row_mask:0xf bank_mask:0xf bound_ctrl:1
	v_add_f32_dpp v180, v160, v160 row_ror:4 row_mask:0xf bank_mask:0xf bound_ctrl:1
	v_pk_fma_f32 v[162:163], v[184:185], v[200:201], v[162:163] op_sel_hi:[1,0,1]
	v_add_f32_dpp v160, v161, v161 row_ror:8 row_mask:0xf bank_mask:0xf bound_ctrl:1
	v_add_f32_dpp v161, v180, v180 row_ror:8 row_mask:0xf bank_mask:0xf bound_ctrl:1
	v_pk_fma_f32 v[196:197], v[192:193], v[160:161], v[162:163] op_sel_hi:[1,0,1]
	v_cndmask_b32_e64 v199, v199, v161, s[26:27]
	v_pk_fma_f32 v[34:35], v[194:195], v[160:161], v[34:35] op_sel_hi:[1,0,1]
	ds_read_b128 v[160:163], v28 offset:19968
	ds_read_b128 v[180:183], v28 offset:20224
	ds_read_b128 v[184:187], v28 offset:20480
	ds_read_b128 v[188:191], v28 offset:20992
	ds_read_b128 v[192:195], v28 offset:21248
	ds_read_b32 v200, v29 offset:20736
	s_waitcnt lgkmcnt(8)
	v_pk_mul_f32 v[174:175], v[174:175], v[34:35]
	v_pk_mul_f32 v[26:27], v[26:27], v[34:35]
	v_pk_fma_f32 v[172:173], v[172:173], v[196:197], v[174:175]
	v_pk_fma_f32 v[24:25], v[24:25], v[196:197], v[26:27]
	v_add_f32_e32 v206, v172, v173
	v_add_f32_e32 v24, v24, v25
	v_pk_mul_f32 v[26:27], v[164:165], v[196:197]
	v_add_f32_dpp v25, v206, v206 quad_perm:[1,0,3,2] row_mask:0xf bank_mask:0xf bound_ctrl:1
	v_add_f32_dpp v24, v24, v24 quad_perm:[1,0,3,2] row_mask:0xf bank_mask:0xf bound_ctrl:1
	v_pk_mul_f32 v[34:35], v[166:167], v[34:35]
	s_waitcnt lgkmcnt(6)
	v_add_f32_dpp v25, v25, v25 quad_perm:[2,3,0,1] row_mask:0xf bank_mask:0xf bound_ctrl:1
	v_add_f32_dpp v24, v24, v24 quad_perm:[2,3,0,1] row_mask:0xf bank_mask:0xf bound_ctrl:1
	v_pk_fma_f32 v[34:35], v[170:171], v[198:199], v[34:35] op_sel_hi:[1,0,1]
	v_add_f32_dpp v25, v25, v25 row_ror:4 row_mask:0xf bank_mask:0xf bound_ctrl:1
	v_add_f32_dpp v164, v24, v24 row_ror:4 row_mask:0xf bank_mask:0xf bound_ctrl:1
	v_pk_fma_f32 v[26:27], v[168:169], v[198:199], v[26:27] op_sel_hi:[1,0,1]
	v_add_f32_dpp v24, v25, v25 row_ror:8 row_mask:0xf bank_mask:0xf bound_ctrl:1
	v_add_f32_dpp v25, v164, v164 row_ror:8 row_mask:0xf bank_mask:0xf bound_ctrl:1
	v_pk_fma_f32 v[196:197], v[176:177], v[24:25], v[26:27] op_sel_hi:[1,0,1]
	v_cndmask_b32_e64 v199, v199, v25, s[28:29]
	v_pk_fma_f32 v[34:35], v[178:179], v[24:25], v[34:35] op_sel_hi:[1,0,1]
	ds_read_b128 v[24:27], v28 offset:21504
	ds_read_b128 v[164:167], v28 offset:21760
	ds_read_b128 v[168:171], v28 offset:22016
	ds_read_b128 v[172:175], v28 offset:22528
	ds_read_b128 v[176:179], v28 offset:22784
	ds_read_b32 v198, v29 offset:22272
	s_waitcnt lgkmcnt(8)
	v_pk_mul_f32 v[190:191], v[190:191], v[34:35]
	v_pk_mul_f32 v[32:33], v[32:33], v[34:35]
	v_pk_fma_f32 v[188:189], v[188:189], v[196:197], v[190:191]
	v_pk_fma_f32 v[30:31], v[30:31], v[196:197], v[32:33]
	v_add_f32_e32 v206, v188, v189
	v_add_f32_e32 v30, v30, v31
	v_pk_mul_f32 v[32:33], v[180:181], v[196:197]
	v_add_f32_dpp v31, v206, v206 quad_perm:[1,0,3,2] row_mask:0xf bank_mask:0xf bound_ctrl:1
	v_add_f32_dpp v30, v30, v30 quad_perm:[1,0,3,2] row_mask:0xf bank_mask:0xf bound_ctrl:1
	v_pk_mul_f32 v[34:35], v[182:183], v[34:35]
	s_waitcnt lgkmcnt(6)
; #define LAS __attribute__((address_space(3)))
; __device__ __forceinline__ void rwkv_scan_prompt(const Params& p, LAS unsigned char* lds, int bh, int rq) {
;     ...
;             for (int tk = 0; tk < TC; ++tk) {
;                 f32x4 nr4 = r4, nd4 = d4, nk4 = k4, na4 = a4, nb4 = b4; float nvv = vv;
;                 if (tk < TC - 1) {
;                     const LAS float* o = ob + (tk + 1) * 6 * 64;
;                     nr4 = *(const LAS f32x4*)(o + cg_ * 4); nd4 = *(const LAS f32x4*)(o + 64 + cg_ * 4); nk4 = *(const LAS f32x4*)(o + 128 + cg_ * 4);
;                     na4 = *(const LAS f32x4*)(o + 256 + cg_ * 4); nb4 = *(const LAS f32x4*)(o + 320 + cg_ * 4);
;                     nvv = o[192 + rq * 16 + rloc];
;                 }
;                 __builtin_amdgcn_sched_barrier(0);
;                 typedef float f32x2_ __attribute__((ext_vector_type(2)));
;                 f32x2_ ta = (f32x2_){S[0], S[1]} * (f32x2_){a4[0], a4[1]}; ta = (f32x2_){S[2], S[3]} * (f32x2_){a4[2], a4[3]} + ta;
;                 f32x2_ ty = (f32x2_){S[0], S[1]} * (f32x2_){rp[0], rp[1]}; ty = (f32x2_){S[2], S[3]} * (f32x2_){rp[2], rp[3]} + ty;
;                 const f32x4 T = S * d4 + vv * k4;
;                 float sa = ta[0] + ta[1];
;                 float yp = ty[0] + ty[1];
;                 sa = dpp_add<0xB1>(sa); yp = dpp_add<0xB1>(yp);
;                 sa = dpp_add<0x4E>(sa); yp = dpp_add<0x4E>(yp);
;                 sa = dpp_add<0x124>(sa); yp = dpp_add<0x124>(yp);
;                 sa = dpp_add<0x128>(sa); yp = dpp_add<0x128>(yp);
;                 if (tk > 0) yk[(tk - 1) >> 4] = (cg_ == ((tk - 1) & 15)) ? yp : yk[(tk - 1) >> 4];
;                 S = sa * b4 + T;
;                 rp = r4;
;                 r4 = nr4; d4 = nd4; k4 = nk4; a4 = na4; b4 = nb4; vv = nvv;
	v_add_f32_dpp v31, v31, v31 quad_perm:[2,3,0,1] row_mask:0xf bank_mask:0xf bound_ctrl:1
	v_add_f32_dpp v30, v30, v30 quad_perm:[2,3,0,1] row_mask:0xf bank_mask:0xf bound_ctrl:1
	v_pk_fma_f32 v[34:35], v[186:187], v[200:201], v[34:35] op_sel_hi:[1,0,1]
	v_add_f32_dpp v31, v31, v31 row_ror:4 row_mask:0xf bank_mask:0xf bound_ctrl:1
	v_add_f32_dpp v180, v30, v30 row_ror:4 row_mask:0xf bank_mask:0xf bound_ctrl:1
	v_pk_fma_f32 v[32:33], v[184:185], v[200:201], v[32:33] op_sel_hi:[1,0,1]
	v_add_f32_dpp v30, v31, v31 row_ror:8 row_mask:0xf bank_mask:0xf bound_ctrl:1
	v_add_f32_dpp v31, v180, v180 row_ror:8 row_mask:0xf bank_mask:0xf bound_ctrl:1
	v_pk_fma_f32 v[196:197], v[192:193], v[30:31], v[32:33] op_sel_hi:[1,0,1]
	v_cndmask_b32_e64 v199, v199, v31, s[30:31]
	v_pk_fma_f32 v[34:35], v[194:195], v[30:31], v[34:35] op_sel_hi:[1,0,1]
	ds_read_b128 v[30:33], v28 offset:23040
	ds_read_b128 v[180:183], v28 offset:23296
	ds_read_b128 v[184:187], v28 offset:23552
	ds_read_b128 v[188:191], v28 offset:24064
	ds_read_b128 v[192:195], v28 offset:24320
	ds_read_b32 v200, v29 offset:23808
	s_waitcnt lgkmcnt(8)
	v_pk_mul_f32 v[174:175], v[174:175], v[34:35]
	v_pk_mul_f32 v[162:163], v[162:163], v[34:35]
	v_pk_fma_f32 v[172:173], v[172:173], v[196:197], v[174:175]
	v_pk_fma_f32 v[160:161], v[160:161], v[196:197], v[162:163]
	v_add_f32_e32 v206, v172, v173
	v_add_f32_e32 v160, v160, v161
	v_pk_mul_f32 v[162:163], v[164:165], v[196:197]
	v_add_f32_dpp v161, v206, v206 quad_perm:[1,0,3,2] row_mask:0xf bank_mask:0xf bound_ctrl:1
	v_add_f32_dpp v160, v160, v160 quad_perm:[1,0,3,2] row_mask:0xf bank_mask:0xf bound_ctrl:1
	v_pk_mul_f32 v[34:35], v[166:167], v[34:35]
	s_waitcnt lgkmcnt(6)
	v_add_f32_dpp v161, v161, v161 quad_perm:[2,3,0,1] row_mask:0xf bank_mask:0xf bound_ctrl:1
	v_add_f32_dpp v160, v160, v160 quad_perm:[2,3,0,1] row_mask:0xf bank_mask:0xf bound_ctrl:1
	v_pk_fma_f32 v[34:35], v[170:171], v[198:199], v[34:35] op_sel_hi:[1,0,1]
	v_add_f32_dpp v161, v161, v161 row_ror:4 row_mask:0xf bank_mask:0xf bound_ctrl:1
	v_add_f32_dpp v164, v160, v160 row_ror:4 row_mask:0xf bank_mask:0xf bound_ctrl:1
	v_pk_fma_f32 v[162:163], v[168:169], v[198:199], v[162:163] op_sel_hi:[1,0,1]
	v_add_f32_dpp v160, v161, v161 row_ror:8 row_mask:0xf bank_mask:0xf bound_ctrl:1
	v_add_f32_dpp v161, v164, v164 row_ror:8 row_mask:0xf bank_mask:0xf bound_ctrl:1
	v_pk_fma_f32 v[196:197], v[176:177], v[160:161], v[162:163] op_sel_hi:[1,0,1]
	v_cndmask_b32_e64 v199, v199, v161, s[34:35]
	v_pk_fma_f32 v[34:35], v[178:179], v[160:161], v[34:35] op_sel_hi:[1,0,1]
	ds_read_b128 v[160:163], v28 offset:24576
	ds_read_b128 v[164:167], v28 offset:24832
	ds_read_b128 v[168:171], v28 offset:25088
	ds_read_b128 v[172:175], v28 offset:25600
	ds_read_b128 v[176:179], v28 offset:25856
	ds_read_b32 v198, v29 offset:25344
	s_waitcnt lgkmcnt(8)
	v_pk_mul_f32 v[190:191], v[190:191], v[34:35]
	v_pk_mul_f32 v[26:27], v[26:27], v[34:35]
	v_pk_fma_f32 v[188:189], v[188:189], v[196:197], v[190:191]
	v_pk_fma_f32 v[24:25], v[24:25], v[196:197], v[26:27]
	v_add_f32_e32 v206, v188, v189
	v_add_f32_e32 v24, v24, v25
	v_pk_mul_f32 v[26:27], v[180:181], v[196:197]
	v_add_f32_dpp v25, v206, v206 quad_perm:[1,0,3,2] row_mask:0xf bank_mask:0xf bound_ctrl:1
	v_add_f32_dpp v24, v24, v24 quad_perm:[1,0,3,2] row_mask:0xf bank_mask:0xf bound_ctrl:1
	v_pk_mul_f32 v[34:35], v[182:183], v[34:35]
	s_waitcnt lgkmcnt(6)
	v_add_f32_dpp v25, v25, v25 quad_perm:[2,3,0,1] row_mask:0xf bank_mask:0xf bound_ctrl:1
	v_add_f32_dpp v24, v24, v24 quad_perm:[2,3,0,1] row_mask:0xf bank_mask:0xf bound_ctrl:1
	v_pk_fma_f32 v[34:35], v[186:187], v[200:201], v[34:35] op_sel_hi:[1,0,1]
	v_add_f32_dpp v25, v25, v25 row_ror:4 row_mask:0xf bank_mask:0xf bound_ctrl:1
	v_add_f32_dpp v180, v24, v24 row_ror:4 row_mask:0xf bank_mask:0xf bound_ctrl:1
	v_pk_fma_f32 v[26:27], v[184:185], v[200:201], v[26:27] op_sel_hi:[1,0,1]
	v_add_f32_dpp v24, v25, v25 row_ror:8 row_mask:0xf bank_mask:0xf bound_ctrl:1
	v_add_f32_dpp v25, v180, v180 row_ror:8 row_mask:0xf bank_mask:0xf bound_ctrl:1
	v_pk_fma_f32 v[196:197], v[192:193], v[24:25], v[26:27] op_sel_hi:[1,0,1]
	v_cndmask_b32_e64 v199, v199, v25, s[36:37]
	v_pk_fma_f32 v[34:35], v[194:195], v[24:25], v[34:35] op_sel_hi:[1,0,1]
	ds_read_b128 v[24:27], v28 offset:26112
	ds_read_b128 v[180:183], v28 offset:26368
	ds_read_b128 v[184:187], v28 offset:26624
	ds_read_b128 v[188:191], v28 offset:27136
	ds_read_b128 v[192:195], v28 offset:27392
	ds_read_b32 v200, v29 offset:26880
	s_waitcnt lgkmcnt(8)
	v_pk_mul_f32 v[174:175], v[174:175], v[34:35]
	v_pk_mul_f32 v[32:33], v[32:33], v[34:35]
	v_pk_fma_f32 v[172:173], v[172:173], v[196:197], v[174:175]
	v_pk_fma_f32 v[30:31], v[30:31], v[196:197], v[32:33]
	v_add_f32_e32 v206, v172, v173
	v_add_f32_e32 v30, v30, v31
	v_pk_mul_f32 v[32:33], v[164:165], v[196:197]
	v_add_f32_dpp v31, v206, v206 quad_perm:[1,0,3,2] row_mask:0xf bank_mask:0xf bound_ctrl:1
	v_add_f32_dpp v30, v30, v30 quad_perm:[1,0,3,2] row_mask:0xf bank_mask:0xf bound_ctrl:1
	v_pk_mul_f32 v[34:35], v[166:167], v[34:35]
	s_waitcnt lgkmcnt(6)
	v_add_f32_dpp v31, v31, v31 quad_perm:[2,3,0,1] row_mask:0xf bank_mask:0xf bound_ctrl:1
	v_add_f32_dpp v30, v30, v30 quad_perm:[2,3,0,1] row_mask:0xf bank_mask:0xf bound_ctrl:1
	v_pk_fma_f32 v[34:35], v[170:171], v[198:199], v[34:35] op_sel_hi:[1,0,1]
	v_add_f32_dpp v31, v31, v31 row_ror:4 row_mask:0xf bank_mask:0xf bound_ctrl:1
	v_add_f32_dpp v30, v30, v30 row_ror:4 row_mask:0xf bank_mask:0xf bound_ctrl:1
	v_pk_fma_f32 v[32:33], v[168:169], v[198:199], v[32:33] op_sel_hi:[1,0,1]
	v_add_f32_dpp v164, v31, v31 row_ror:8 row_mask:0xf bank_mask:0xf bound_ctrl:1
	v_add_f32_dpp v30, v30, v30 row_ror:8 row_mask:0xf bank_mask:0xf bound_ctrl:1
	v_pk_fma_f32 v[196:197], v[176:177], v[164:165], v[32:33] op_sel_hi:[1,0,1]
	v_cndmask_b32_e64 v30, v199, v30, s[4:5]
	v_pk_fma_f32 v[198:199], v[178:179], v[164:165], v[34:35] op_sel_hi:[1,0,1]
	ds_read_b128 v[32:35], v28 offset:27648
	ds_read_b128 v[164:167], v28 offset:27904
	ds_read_b128 v[168:171], v28 offset:28160
	ds_read_b128 v[172:175], v28 offset:28672
	ds_read_b128 v[176:179], v28 offset:28928
	ds_read_b32 v202, v29 offset:28416
	s_waitcnt lgkmcnt(8)
; #define LAS __attribute__((address_space(3)))
; __device__ __forceinline__ void rwkv_scan_prompt(const Params& p, LAS unsigned char* lds, int bh, int rq) {
;     ...
;             for (int tk = 0; tk < TC; ++tk) {
;                 f32x4 nr4 = r4, nd4 = d4, nk4 = k4, na4 = a4, nb4 = b4; float nvv = vv;
;                 if (tk < TC - 1) {
;                     const LAS float* o = ob + (tk + 1) * 6 * 64;
;                     nr4 = *(const LAS f32x4*)(o + cg_ * 4); nd4 = *(const LAS f32x4*)(o + 64 + cg_ * 4); nk4 = *(const LAS f32x4*)(o + 128 + cg_ * 4);
;                     na4 = *(const LAS f32x4*)(o + 256 + cg_ * 4); nb4 = *(const LAS f32x4*)(o + 320 + cg_ * 4);
;                     nvv = o[192 + rq * 16 + rloc];
;                 }
;                 __builtin_amdgcn_sched_barrier(0);
;                 typedef float f32x2_ __attribute__((ext_vector_type(2)));
;                 f32x2_ ta = (f32x2_){S[0], S[1]} * (f32x2_){a4[0], a4[1]}; ta = (f32x2_){S[2], S[3]} * (f32x2_){a4[2], a4[3]} + ta;
;                 f32x2_ ty = (f32x2_){S[0], S[1]} * (f32x2_){rp[0], rp[1]}; ty = (f32x2_){S[2], S[3]} * (f32x2_){rp[2], rp[3]} + ty;
;                 const f32x4 T = S * d4 + vv * k4;
;                 float sa = ta[0] + ta[1];
;                 float yp = ty[0] + ty[1];
;                 sa = dpp_add<0xB1>(sa); yp = dpp_add<0xB1>(yp);
;                 sa = dpp_add<0x4E>(sa); yp = dpp_add<0x4E>(yp);
;                 sa = dpp_add<0x124>(sa); yp = dpp_add<0x124>(yp);
;                 sa = dpp_add<0x128>(sa); yp = dpp_add<0x128>(yp);
;                 if (tk > 0) yk[(tk - 1) >> 4] = (cg_ == ((tk - 1) & 15)) ? yp : yk[(tk - 1) >> 4];
;                 S = sa * b4 + T;
;                 rp = r4;
;                 r4 = nr4; d4 = nd4; k4 = nk4; a4 = na4; b4 = nb4; vv = nvv;
	v_pk_mul_f32 v[190:191], v[190:191], v[198:199]
	v_pk_mul_f32 v[162:163], v[162:163], v[198:199]
	v_pk_fma_f32 v[188:189], v[188:189], v[196:197], v[190:191]
	v_pk_fma_f32 v[160:161], v[160:161], v[196:197], v[162:163]
	v_add_f32_e32 v31, v188, v189
	v_add_f32_e32 v160, v160, v161
	v_pk_mul_f32 v[162:163], v[180:181], v[196:197]
	v_add_f32_dpp v31, v31, v31 quad_perm:[1,0,3,2] row_mask:0xf bank_mask:0xf bound_ctrl:1
	v_add_f32_dpp v160, v160, v160 quad_perm:[1,0,3,2] row_mask:0xf bank_mask:0xf bound_ctrl:1
	v_pk_mul_f32 v[180:181], v[182:183], v[198:199]
	v_add_f32_dpp v31, v31, v31 quad_perm:[2,3,0,1] row_mask:0xf bank_mask:0xf bound_ctrl:1
	v_add_f32_dpp v160, v160, v160 quad_perm:[2,3,0,1] row_mask:0xf bank_mask:0xf bound_ctrl:1
	s_waitcnt lgkmcnt(6)
	v_pk_fma_f32 v[180:181], v[186:187], v[200:201], v[180:181] op_sel_hi:[1,0,1]
	v_add_f32_dpp v31, v31, v31 row_ror:4 row_mask:0xf bank_mask:0xf bound_ctrl:1
	v_pk_fma_f32 v[162:163], v[184:185], v[200:201], v[162:163] op_sel_hi:[1,0,1]
	v_add_f32_dpp v161, v160, v160 row_ror:4 row_mask:0xf bank_mask:0xf bound_ctrl:1
	v_add_f32_dpp v160, v31, v31 row_ror:8 row_mask:0xf bank_mask:0xf bound_ctrl:1
	v_pk_fma_f32 v[196:197], v[192:193], v[160:161], v[162:163] op_sel_hi:[1,0,1]
	v_add_f32_dpp v31, v161, v161 row_ror:8 row_mask:0xf bank_mask:0xf bound_ctrl:1
	v_pk_fma_f32 v[198:199], v[194:195], v[160:161], v[180:181] op_sel_hi:[1,0,1]
	ds_read_b128 v[160:163], v28 offset:29184
	ds_read_b128 v[180:183], v28 offset:29440
	ds_read_b128 v[184:187], v28 offset:29696
	ds_read_b128 v[188:191], v28 offset:30208
	ds_read_b128 v[192:195], v28 offset:30464
	ds_read_b32 v200, v29 offset:29952
	v_cndmask_b32_e64 v31, 0, v31, s[6:7]
	s_waitcnt lgkmcnt(8)
	v_pk_mul_f32 v[174:175], v[174:175], v[198:199]
	v_pk_mul_f32 v[26:27], v[26:27], v[198:199]
	v_pk_fma_f32 v[172:173], v[172:173], v[196:197], v[174:175]
	v_pk_fma_f32 v[24:25], v[24:25], v[196:197], v[26:27]
	v_add_f32_e32 v206, v172, v173
	v_add_f32_e32 v24, v24, v25
	v_pk_mul_f32 v[26:27], v[164:165], v[196:197]
	s_waitcnt lgkmcnt(6)
	v_add_f32_dpp v25, v206, v206 quad_perm:[1,0,3,2] row_mask:0xf bank_mask:0xf bound_ctrl:1
	v_add_f32_dpp v24, v24, v24 quad_perm:[1,0,3,2] row_mask:0xf bank_mask:0xf bound_ctrl:1
	v_pk_mul_f32 v[164:165], v[166:167], v[198:199]
	v_add_f32_dpp v25, v25, v25 quad_perm:[2,3,0,1] row_mask:0xf bank_mask:0xf bound_ctrl:1
	v_add_f32_dpp v24, v24, v24 quad_perm:[2,3,0,1] row_mask:0xf bank_mask:0xf bound_ctrl:1
	v_pk_fma_f32 v[164:165], v[170:171], v[202:203], v[164:165] op_sel_hi:[1,0,1]
	v_add_f32_dpp v25, v25, v25 row_ror:4 row_mask:0xf bank_mask:0xf bound_ctrl:1
	v_add_f32_dpp v166, v24, v24 row_ror:4 row_mask:0xf bank_mask:0xf bound_ctrl:1
	v_pk_fma_f32 v[26:27], v[168:169], v[202:203], v[26:27] op_sel_hi:[1,0,1]
	v_add_f32_dpp v24, v25, v25 row_ror:8 row_mask:0xf bank_mask:0xf bound_ctrl:1
	v_add_f32_dpp v25, v166, v166 row_ror:8 row_mask:0xf bank_mask:0xf bound_ctrl:1
	v_pk_fma_f32 v[196:197], v[176:177], v[24:25], v[26:27] op_sel_hi:[1,0,1]
	v_cndmask_b32_e64 v31, v31, v25, s[8:9]
	v_pk_fma_f32 v[198:199], v[178:179], v[24:25], v[164:165] op_sel_hi:[1,0,1]
	ds_read_b128 v[24:27], v28 offset:30720
	ds_read_b128 v[164:167], v28 offset:30976
	ds_read_b128 v[168:171], v28 offset:31232
	ds_read_b128 v[172:175], v28 offset:31744
	ds_read_b128 v[176:179], v28 offset:32000
	ds_read_b32 v202, v29 offset:31488
	s_waitcnt lgkmcnt(8)
	v_pk_mul_f32 v[190:191], v[190:191], v[198:199]
	v_pk_mul_f32 v[34:35], v[34:35], v[198:199]
	v_pk_fma_f32 v[188:189], v[188:189], v[196:197], v[190:191]
	v_pk_fma_f32 v[32:33], v[32:33], v[196:197], v[34:35]
	v_add_f32_e32 v206, v188, v189
	v_add_f32_e32 v32, v32, v33
	v_pk_mul_f32 v[34:35], v[180:181], v[196:197]
	s_waitcnt lgkmcnt(6)
	v_add_f32_dpp v33, v206, v206 quad_perm:[1,0,3,2] row_mask:0xf bank_mask:0xf bound_ctrl:1
	v_add_f32_dpp v32, v32, v32 quad_perm:[1,0,3,2] row_mask:0xf bank_mask:0xf bound_ctrl:1
	v_pk_mul_f32 v[180:181], v[182:183], v[198:199]
	v_add_f32_dpp v33, v33, v33 quad_perm:[2,3,0,1] row_mask:0xf bank_mask:0xf bound_ctrl:1
	v_add_f32_dpp v32, v32, v32 quad_perm:[2,3,0,1] row_mask:0xf bank_mask:0xf bound_ctrl:1
	v_pk_fma_f32 v[180:181], v[186:187], v[200:201], v[180:181] op_sel_hi:[1,0,1]
	v_add_f32_dpp v33, v33, v33 row_ror:4 row_mask:0xf bank_mask:0xf bound_ctrl:1
	v_add_f32_dpp v182, v32, v32 row_ror:4 row_mask:0xf bank_mask:0xf bound_ctrl:1
	v_pk_fma_f32 v[34:35], v[184:185], v[200:201], v[34:35] op_sel_hi:[1,0,1]
	v_add_f32_dpp v32, v33, v33 row_ror:8 row_mask:0xf bank_mask:0xf bound_ctrl:1
	v_add_f32_dpp v33, v182, v182 row_ror:8 row_mask:0xf bank_mask:0xf bound_ctrl:1
	v_pk_fma_f32 v[196:197], v[192:193], v[32:33], v[34:35] op_sel_hi:[1,0,1]
	v_cndmask_b32_e64 v31, v31, v33, s[10:11]
	v_pk_fma_f32 v[198:199], v[194:195], v[32:33], v[180:181] op_sel_hi:[1,0,1]
	ds_read_b128 v[32:35], v28 offset:32256
	ds_read_b128 v[180:183], v28 offset:32512
	ds_read_b128 v[184:187], v28 offset:32768
	ds_read_b128 v[188:191], v28 offset:33280
	ds_read_b128 v[192:195], v28 offset:33536
	ds_read_b32 v200, v29 offset:33024
	s_waitcnt lgkmcnt(8)
	v_pk_mul_f32 v[174:175], v[174:175], v[198:199]
	v_pk_mul_f32 v[162:163], v[162:163], v[198:199]
	v_pk_fma_f32 v[172:173], v[172:173], v[196:197], v[174:175]
	v_pk_fma_f32 v[160:161], v[160:161], v[196:197], v[162:163]
	v_add_f32_e32 v206, v172, v173
	v_add_f32_e32 v160, v160, v161
	v_pk_mul_f32 v[162:163], v[164:165], v[196:197]
	s_waitcnt lgkmcnt(6)
; #define LAS __attribute__((address_space(3)))
; __device__ __forceinline__ void rwkv_scan_prompt(const Params& p, LAS unsigned char* lds, int bh, int rq) {
;     ...
;             for (int tk = 0; tk < TC; ++tk) {
;                 f32x4 nr4 = r4, nd4 = d4, nk4 = k4, na4 = a4, nb4 = b4; float nvv = vv;
;                 if (tk < TC - 1) {
;                     const LAS float* o = ob + (tk + 1) * 6 * 64;
;                     nr4 = *(const LAS f32x4*)(o + cg_ * 4); nd4 = *(const LAS f32x4*)(o + 64 + cg_ * 4); nk4 = *(const LAS f32x4*)(o + 128 + cg_ * 4);
;                     na4 = *(const LAS f32x4*)(o + 256 + cg_ * 4); nb4 = *(const LAS f32x4*)(o + 320 + cg_ * 4);
;                     nvv = o[192 + rq * 16 + rloc];
;                 }
;                 __builtin_amdgcn_sched_barrier(0);
;                 typedef float f32x2_ __attribute__((ext_vector_type(2)));
;                 f32x2_ ta = (f32x2_){S[0], S[1]} * (f32x2_){a4[0], a4[1]}; ta = (f32x2_){S[2], S[3]} * (f32x2_){a4[2], a4[3]} + ta;
;                 f32x2_ ty = (f32x2_){S[0], S[1]} * (f32x2_){rp[0], rp[1]}; ty = (f32x2_){S[2], S[3]} * (f32x2_){rp[2], rp[3]} + ty;
;                 const f32x4 T = S * d4 + vv * k4;
;                 float sa = ta[0] + ta[1];
;                 float yp = ty[0] + ty[1];
;                 sa = dpp_add<0xB1>(sa); yp = dpp_add<0xB1>(yp);
;                 sa = dpp_add<0x4E>(sa); yp = dpp_add<0x4E>(yp);
;                 sa = dpp_add<0x124>(sa); yp = dpp_add<0x124>(yp);
;                 sa = dpp_add<0x128>(sa); yp = dpp_add<0x128>(yp);
;                 if (tk > 0) yk[(tk - 1) >> 4] = (cg_ == ((tk - 1) & 15)) ? yp : yk[(tk - 1) >> 4];
;                 S = sa * b4 + T;
;                 rp = r4;
;                 r4 = nr4; d4 = nd4; k4 = nk4; a4 = na4; b4 = nb4; vv = nvv;
	v_add_f32_dpp v161, v206, v206 quad_perm:[1,0,3,2] row_mask:0xf bank_mask:0xf bound_ctrl:1
	v_add_f32_dpp v160, v160, v160 quad_perm:[1,0,3,2] row_mask:0xf bank_mask:0xf bound_ctrl:1
	v_pk_mul_f32 v[164:165], v[166:167], v[198:199]
	v_add_f32_dpp v161, v161, v161 quad_perm:[2,3,0,1] row_mask:0xf bank_mask:0xf bound_ctrl:1
	v_add_f32_dpp v160, v160, v160 quad_perm:[2,3,0,1] row_mask:0xf bank_mask:0xf bound_ctrl:1
	v_pk_fma_f32 v[164:165], v[170:171], v[202:203], v[164:165] op_sel_hi:[1,0,1]
	v_add_f32_dpp v161, v161, v161 row_ror:4 row_mask:0xf bank_mask:0xf bound_ctrl:1
	v_add_f32_dpp v166, v160, v160 row_ror:4 row_mask:0xf bank_mask:0xf bound_ctrl:1
	v_pk_fma_f32 v[162:163], v[168:169], v[202:203], v[162:163] op_sel_hi:[1,0,1]
	v_add_f32_dpp v160, v161, v161 row_ror:8 row_mask:0xf bank_mask:0xf bound_ctrl:1
	v_add_f32_dpp v161, v166, v166 row_ror:8 row_mask:0xf bank_mask:0xf bound_ctrl:1
	v_pk_fma_f32 v[196:197], v[176:177], v[160:161], v[162:163] op_sel_hi:[1,0,1]
	v_cndmask_b32_e64 v31, v31, v161, s[12:13]
	v_pk_fma_f32 v[198:199], v[178:179], v[160:161], v[164:165] op_sel_hi:[1,0,1]
	ds_read_b128 v[160:163], v28 offset:33792
	ds_read_b128 v[164:167], v28 offset:34048
	ds_read_b128 v[168:171], v28 offset:34304
	ds_read_b128 v[172:175], v28 offset:34816
	ds_read_b128 v[176:179], v28 offset:35072
	ds_read_b32 v202, v29 offset:34560
	s_waitcnt lgkmcnt(8)
	v_pk_mul_f32 v[190:191], v[190:191], v[198:199]
	v_pk_mul_f32 v[26:27], v[26:27], v[198:199]
	v_pk_fma_f32 v[188:189], v[188:189], v[196:197], v[190:191]
	v_pk_fma_f32 v[24:25], v[24:25], v[196:197], v[26:27]
	v_add_f32_e32 v206, v188, v189
	v_add_f32_e32 v24, v24, v25
	v_pk_mul_f32 v[26:27], v[180:181], v[196:197]
	s_waitcnt lgkmcnt(6)
	v_add_f32_dpp v25, v206, v206 quad_perm:[1,0,3,2] row_mask:0xf bank_mask:0xf bound_ctrl:1
	v_add_f32_dpp v24, v24, v24 quad_perm:[1,0,3,2] row_mask:0xf bank_mask:0xf bound_ctrl:1
	v_pk_mul_f32 v[180:181], v[182:183], v[198:199]
	v_add_f32_dpp v25, v25, v25 quad_perm:[2,3,0,1] row_mask:0xf bank_mask:0xf bound_ctrl:1
	v_add_f32_dpp v24, v24, v24 quad_perm:[2,3,0,1] row_mask:0xf bank_mask:0xf bound_ctrl:1
	v_pk_fma_f32 v[180:181], v[186:187], v[200:201], v[180:181] op_sel_hi:[1,0,1]
	v_add_f32_dpp v25, v25, v25 row_ror:4 row_mask:0xf bank_mask:0xf bound_ctrl:1
	v_add_f32_dpp v182, v24, v24 row_ror:4 row_mask:0xf bank_mask:0xf bound_ctrl:1
	v_pk_fma_f32 v[26:27], v[184:185], v[200:201], v[26:27] op_sel_hi:[1,0,1]
	v_add_f32_dpp v24, v25, v25 row_ror:8 row_mask:0xf bank_mask:0xf bound_ctrl:1
	v_add_f32_dpp v25, v182, v182 row_ror:8 row_mask:0xf bank_mask:0xf bound_ctrl:1
	v_pk_fma_f32 v[196:197], v[192:193], v[24:25], v[26:27] op_sel_hi:[1,0,1]
	v_cndmask_b32_e64 v31, v31, v25, s[14:15]
	v_pk_fma_f32 v[198:199], v[194:195], v[24:25], v[180:181] op_sel_hi:[1,0,1]
	ds_read_b128 v[24:27], v28 offset:35328
	ds_read_b128 v[180:183], v28 offset:35584
	ds_read_b128 v[184:187], v28 offset:35840
	ds_read_b128 v[188:191], v28 offset:36352
	ds_read_b128 v[192:195], v28 offset:36608
	ds_read_b32 v200, v29 offset:36096
	s_waitcnt lgkmcnt(8)
	v_pk_mul_f32 v[174:175], v[174:175], v[198:199]
	v_pk_mul_f32 v[34:35], v[34:35], v[198:199]
	v_pk_fma_f32 v[172:173], v[172:173], v[196:197], v[174:175]
	v_pk_fma_f32 v[32:33], v[32:33], v[196:197], v[34:35]
	v_add_f32_e32 v206, v172, v173
	v_add_f32_e32 v32, v32, v33
	v_pk_mul_f32 v[34:35], v[164:165], v[196:197]
	s_waitcnt lgkmcnt(6)
	v_add_f32_dpp v33, v206, v206 quad_perm:[1,0,3,2] row_mask:0xf bank_mask:0xf bound_ctrl:1
	v_add_f32_dpp v32, v32, v32 quad_perm:[1,0,3,2] row_mask:0xf bank_mask:0xf bound_ctrl:1
	v_pk_mul_f32 v[164:165], v[166:167], v[198:199]
	v_add_f32_dpp v33, v33, v33 quad_perm:[2,3,0,1] row_mask:0xf bank_mask:0xf bound_ctrl:1
	v_add_f32_dpp v32, v32, v32 quad_perm:[2,3,0,1] row_mask:0xf bank_mask:0xf bound_ctrl:1
	v_pk_fma_f32 v[164:165], v[170:171], v[202:203], v[164:165] op_sel_hi:[1,0,1]
	v_add_f32_dpp v33, v33, v33 row_ror:4 row_mask:0xf bank_mask:0xf bound_ctrl:1
	v_add_f32_dpp v166, v32, v32 row_ror:4 row_mask:0xf bank_mask:0xf bound_ctrl:1
	v_pk_fma_f32 v[34:35], v[168:169], v[202:203], v[34:35] op_sel_hi:[1,0,1]
	v_add_f32_dpp v32, v33, v33 row_ror:8 row_mask:0xf bank_mask:0xf bound_ctrl:1
	v_add_f32_dpp v33, v166, v166 row_ror:8 row_mask:0xf bank_mask:0xf bound_ctrl:1
	v_pk_fma_f32 v[196:197], v[176:177], v[32:33], v[34:35] op_sel_hi:[1,0,1]
	v_cndmask_b32_e64 v31, v31, v33, s[16:17]
	v_pk_fma_f32 v[198:199], v[178:179], v[32:33], v[164:165] op_sel_hi:[1,0,1]
	ds_read_b128 v[32:35], v28 offset:36864
	ds_read_b128 v[164:167], v28 offset:37120
	ds_read_b128 v[168:171], v28 offset:37376
	ds_read_b128 v[172:175], v28 offset:37888
	ds_read_b128 v[176:179], v28 offset:38144
	ds_read_b32 v202, v29 offset:37632
	s_waitcnt lgkmcnt(8)
	v_pk_mul_f32 v[190:191], v[190:191], v[198:199]
	v_pk_mul_f32 v[162:163], v[162:163], v[198:199]
	v_pk_fma_f32 v[188:189], v[188:189], v[196:197], v[190:191]
	v_pk_fma_f32 v[160:161], v[160:161], v[196:197], v[162:163]
	v_add_f32_e32 v206, v188, v189
	v_add_f32_e32 v160, v160, v161
	v_pk_mul_f32 v[162:163], v[180:181], v[196:197]
	s_waitcnt lgkmcnt(6)
; #define LAS __attribute__((address_space(3)))
; __device__ __forceinline__ void rwkv_scan_prompt(const Params& p, LAS unsigned char* lds, int bh, int rq) {
;     ...
;             for (int tk = 0; tk < TC; ++tk) {
;                 f32x4 nr4 = r4, nd4 = d4, nk4 = k4, na4 = a4, nb4 = b4; float nvv = vv;
;                 if (tk < TC - 1) {
;                     const LAS float* o = ob + (tk + 1) * 6 * 64;
;                     nr4 = *(const LAS f32x4*)(o + cg_ * 4); nd4 = *(const LAS f32x4*)(o + 64 + cg_ * 4); nk4 = *(const LAS f32x4*)(o + 128 + cg_ * 4);
;                     na4 = *(const LAS f32x4*)(o + 256 + cg_ * 4); nb4 = *(const LAS f32x4*)(o + 320 + cg_ * 4);
;                     nvv = o[192 + rq * 16 + rloc];
;                 }
;                 __builtin_amdgcn_sched_barrier(0);
;                 typedef float f32x2_ __attribute__((ext_vector_type(2)));
;                 f32x2_ ta = (f32x2_){S[0], S[1]} * (f32x2_){a4[0], a4[1]}; ta = (f32x2_){S[2], S[3]} * (f32x2_){a4[2], a4[3]} + ta;
;                 f32x2_ ty = (f32x2_){S[0], S[1]} * (f32x2_){rp[0], rp[1]}; ty = (f32x2_){S[2], S[3]} * (f32x2_){rp[2], rp[3]} + ty;
;                 const f32x4 T = S * d4 + vv * k4;
;                 float sa = ta[0] + ta[1];
;                 float yp = ty[0] + ty[1];
;                 sa = dpp_add<0xB1>(sa); yp = dpp_add<0xB1>(yp);
;                 sa = dpp_add<0x4E>(sa); yp = dpp_add<0x4E>(yp);
;                 sa = dpp_add<0x124>(sa); yp = dpp_add<0x124>(yp);
;                 sa = dpp_add<0x128>(sa); yp = dpp_add<0x128>(yp);
;                 if (tk > 0) yk[(tk - 1) >> 4] = (cg_ == ((tk - 1) & 15)) ? yp : yk[(tk - 1) >> 4];
;                 S = sa * b4 + T;
;                 rp = r4;
;                 r4 = nr4; d4 = nd4; k4 = nk4; a4 = na4; b4 = nb4; vv = nvv;
	v_add_f32_dpp v161, v206, v206 quad_perm:[1,0,3,2] row_mask:0xf bank_mask:0xf bound_ctrl:1
	v_add_f32_dpp v160, v160, v160 quad_perm:[1,0,3,2] row_mask:0xf bank_mask:0xf bound_ctrl:1
	v_pk_mul_f32 v[180:181], v[182:183], v[198:199]
	v_add_f32_dpp v161, v161, v161 quad_perm:[2,3,0,1] row_mask:0xf bank_mask:0xf bound_ctrl:1
	v_add_f32_dpp v160, v160, v160 quad_perm:[2,3,0,1] row_mask:0xf bank_mask:0xf bound_ctrl:1
	v_pk_fma_f32 v[180:181], v[186:187], v[200:201], v[180:181] op_sel_hi:[1,0,1]
	v_add_f32_dpp v161, v161, v161 row_ror:4 row_mask:0xf bank_mask:0xf bound_ctrl:1
	v_add_f32_dpp v182, v160, v160 row_ror:4 row_mask:0xf bank_mask:0xf bound_ctrl:1
	v_pk_fma_f32 v[162:163], v[184:185], v[200:201], v[162:163] op_sel_hi:[1,0,1]
	v_add_f32_dpp v160, v161, v161 row_ror:8 row_mask:0xf bank_mask:0xf bound_ctrl:1
	v_add_f32_dpp v161, v182, v182 row_ror:8 row_mask:0xf bank_mask:0xf bound_ctrl:1
	v_pk_fma_f32 v[196:197], v[192:193], v[160:161], v[162:163] op_sel_hi:[1,0,1]
	v_cndmask_b32_e64 v31, v31, v161, s[18:19]
	v_pk_fma_f32 v[198:199], v[194:195], v[160:161], v[180:181] op_sel_hi:[1,0,1]
	ds_read_b128 v[160:163], v28 offset:38400
	ds_read_b128 v[180:183], v28 offset:38656
	ds_read_b128 v[184:187], v28 offset:38912
	ds_read_b128 v[188:191], v28 offset:39424
	ds_read_b128 v[192:195], v28 offset:39680
	ds_read_b32 v200, v29 offset:39168
	s_waitcnt lgkmcnt(8)
	v_pk_mul_f32 v[174:175], v[174:175], v[198:199]
	v_pk_mul_f32 v[26:27], v[26:27], v[198:199]
	v_pk_fma_f32 v[172:173], v[172:173], v[196:197], v[174:175]
	v_pk_fma_f32 v[24:25], v[24:25], v[196:197], v[26:27]
	v_add_f32_e32 v206, v172, v173
	v_add_f32_e32 v24, v24, v25
	v_pk_mul_f32 v[26:27], v[164:165], v[196:197]
	s_waitcnt lgkmcnt(6)
	v_add_f32_dpp v25, v206, v206 quad_perm:[1,0,3,2] row_mask:0xf bank_mask:0xf bound_ctrl:1
	v_add_f32_dpp v24, v24, v24 quad_perm:[1,0,3,2] row_mask:0xf bank_mask:0xf bound_ctrl:1
	v_pk_mul_f32 v[164:165], v[166:167], v[198:199]
	v_add_f32_dpp v25, v25, v25 quad_perm:[2,3,0,1] row_mask:0xf bank_mask:0xf bound_ctrl:1
	v_add_f32_dpp v24, v24, v24 quad_perm:[2,3,0,1] row_mask:0xf bank_mask:0xf bound_ctrl:1
	v_pk_fma_f32 v[164:165], v[170:171], v[202:203], v[164:165] op_sel_hi:[1,0,1]
	v_add_f32_dpp v25, v25, v25 row_ror:4 row_mask:0xf bank_mask:0xf bound_ctrl:1
	v_add_f32_dpp v166, v24, v24 row_ror:4 row_mask:0xf bank_mask:0xf bound_ctrl:1
	v_pk_fma_f32 v[26:27], v[168:169], v[202:203], v[26:27] op_sel_hi:[1,0,1]
	v_add_f32_dpp v24, v25, v25 row_ror:8 row_mask:0xf bank_mask:0xf bound_ctrl:1
	v_add_f32_dpp v25, v166, v166 row_ror:8 row_mask:0xf bank_mask:0xf bound_ctrl:1
	v_pk_fma_f32 v[196:197], v[176:177], v[24:25], v[26:27] op_sel_hi:[1,0,1]
	v_cndmask_b32_e64 v31, v31, v25, s[20:21]
	v_pk_fma_f32 v[198:199], v[178:179], v[24:25], v[164:165] op_sel_hi:[1,0,1]
	ds_read_b128 v[24:27], v28 offset:39936
	ds_read_b128 v[164:167], v28 offset:40192
	ds_read_b128 v[168:171], v28 offset:40448
	ds_read_b128 v[172:175], v28 offset:40960
	ds_read_b128 v[176:179], v28 offset:41216
	ds_read_b32 v202, v29 offset:40704
	s_waitcnt lgkmcnt(8)
	v_pk_mul_f32 v[190:191], v[190:191], v[198:199]
	v_pk_mul_f32 v[34:35], v[34:35], v[198:199]
	v_pk_fma_f32 v[188:189], v[188:189], v[196:197], v[190:191]
	v_pk_fma_f32 v[32:33], v[32:33], v[196:197], v[34:35]
	v_add_f32_e32 v206, v188, v189
	v_add_f32_e32 v32, v32, v33
	v_pk_mul_f32 v[34:35], v[180:181], v[196:197]
	s_waitcnt lgkmcnt(6)
	v_add_f32_dpp v33, v206, v206 quad_perm:[1,0,3,2] row_mask:0xf bank_mask:0xf bound_ctrl:1
	v_add_f32_dpp v32, v32, v32 quad_perm:[1,0,3,2] row_mask:0xf bank_mask:0xf bound_ctrl:1
	v_pk_mul_f32 v[180:181], v[182:183], v[198:199]
	v_add_f32_dpp v33, v33, v33 quad_perm:[2,3,0,1] row_mask:0xf bank_mask:0xf bound_ctrl:1
	v_add_f32_dpp v32, v32, v32 quad_perm:[2,3,0,1] row_mask:0xf bank_mask:0xf bound_ctrl:1
	v_pk_fma_f32 v[180:181], v[186:187], v[200:201], v[180:181] op_sel_hi:[1,0,1]
	v_add_f32_dpp v33, v33, v33 row_ror:4 row_mask:0xf bank_mask:0xf bound_ctrl:1
	v_add_f32_dpp v182, v32, v32 row_ror:4 row_mask:0xf bank_mask:0xf bound_ctrl:1
	v_pk_fma_f32 v[34:35], v[184:185], v[200:201], v[34:35] op_sel_hi:[1,0,1]
	v_add_f32_dpp v32, v33, v33 row_ror:8 row_mask:0xf bank_mask:0xf bound_ctrl:1
	v_add_f32_dpp v33, v182, v182 row_ror:8 row_mask:0xf bank_mask:0xf bound_ctrl:1
	v_pk_fma_f32 v[196:197], v[192:193], v[32:33], v[34:35] op_sel_hi:[1,0,1]
	v_cndmask_b32_e64 v31, v31, v33, s[22:23]
	v_pk_fma_f32 v[198:199], v[194:195], v[32:33], v[180:181] op_sel_hi:[1,0,1]
	ds_read_b128 v[32:35], v28 offset:41472
	ds_read_b128 v[180:183], v28 offset:41728
	ds_read_b128 v[184:187], v28 offset:41984
	ds_read_b128 v[188:191], v28 offset:42496
	ds_read_b128 v[192:195], v28 offset:42752
	ds_read_b32 v200, v29 offset:42240
	s_waitcnt lgkmcnt(8)
	v_pk_mul_f32 v[174:175], v[174:175], v[198:199]
	v_pk_mul_f32 v[162:163], v[162:163], v[198:199]
	v_pk_fma_f32 v[172:173], v[172:173], v[196:197], v[174:175]
	v_pk_fma_f32 v[160:161], v[160:161], v[196:197], v[162:163]
	v_add_f32_e32 v206, v172, v173
	v_add_f32_e32 v160, v160, v161
	v_pk_mul_f32 v[162:163], v[164:165], v[196:197]
	s_waitcnt lgkmcnt(6)
; #define LAS __attribute__((address_space(3)))
; __device__ __forceinline__ void rwkv_scan_prompt(const Params& p, LAS unsigned char* lds, int bh, int rq) {
;     ...
;             for (int tk = 0; tk < TC; ++tk) {
;                 f32x4 nr4 = r4, nd4 = d4, nk4 = k4, na4 = a4, nb4 = b4; float nvv = vv;
;                 if (tk < TC - 1) {
;                     const LAS float* o = ob + (tk + 1) * 6 * 64;
;                     nr4 = *(const LAS f32x4*)(o + cg_ * 4); nd4 = *(const LAS f32x4*)(o + 64 + cg_ * 4); nk4 = *(const LAS f32x4*)(o + 128 + cg_ * 4);
;                     na4 = *(const LAS f32x4*)(o + 256 + cg_ * 4); nb4 = *(const LAS f32x4*)(o + 320 + cg_ * 4);
;                     nvv = o[192 + rq * 16 + rloc];
;                 }
;                 __builtin_amdgcn_sched_barrier(0);
;                 typedef float f32x2_ __attribute__((ext_vector_type(2)));
;                 f32x2_ ta = (f32x2_){S[0], S[1]} * (f32x2_){a4[0], a4[1]}; ta = (f32x2_){S[2], S[3]} * (f32x2_){a4[2], a4[3]} + ta;
;                 f32x2_ ty = (f32x2_){S[0], S[1]} * (f32x2_){rp[0], rp[1]}; ty = (f32x2_){S[2], S[3]} * (f32x2_){rp[2], rp[3]} + ty;
;                 const f32x4 T = S * d4 + vv * k4;
;                 float sa = ta[0] + ta[1];
;                 float yp = ty[0] + ty[1];
;                 sa = dpp_add<0xB1>(sa); yp = dpp_add<0xB1>(yp);
;                 sa = dpp_add<0x4E>(sa); yp = dpp_add<0x4E>(yp);
;                 sa = dpp_add<0x124>(sa); yp = dpp_add<0x124>(yp);
;                 sa = dpp_add<0x128>(sa); yp = dpp_add<0x128>(yp);
;                 if (tk > 0) yk[(tk - 1) >> 4] = (cg_ == ((tk - 1) & 15)) ? yp : yk[(tk - 1) >> 4];
;                 S = sa * b4 + T;
;                 rp = r4;
;                 r4 = nr4; d4 = nd4; k4 = nk4; a4 = na4; b4 = nb4; vv = nvv;
	v_add_f32_dpp v161, v206, v206 quad_perm:[1,0,3,2] row_mask:0xf bank_mask:0xf bound_ctrl:1
	v_add_f32_dpp v160, v160, v160 quad_perm:[1,0,3,2] row_mask:0xf bank_mask:0xf bound_ctrl:1
	v_pk_mul_f32 v[164:165], v[166:167], v[198:199]
	v_add_f32_dpp v161, v161, v161 quad_perm:[2,3,0,1] row_mask:0xf bank_mask:0xf bound_ctrl:1
	v_add_f32_dpp v160, v160, v160 quad_perm:[2,3,0,1] row_mask:0xf bank_mask:0xf bound_ctrl:1
	v_pk_fma_f32 v[164:165], v[170:171], v[202:203], v[164:165] op_sel_hi:[1,0,1]
	v_add_f32_dpp v161, v161, v161 row_ror:4 row_mask:0xf bank_mask:0xf bound_ctrl:1
	v_add_f32_dpp v166, v160, v160 row_ror:4 row_mask:0xf bank_mask:0xf bound_ctrl:1
	v_pk_fma_f32 v[162:163], v[168:169], v[202:203], v[162:163] op_sel_hi:[1,0,1]
	v_add_f32_dpp v160, v161, v161 row_ror:8 row_mask:0xf bank_mask:0xf bound_ctrl:1
	v_add_f32_dpp v161, v166, v166 row_ror:8 row_mask:0xf bank_mask:0xf bound_ctrl:1
	v_pk_fma_f32 v[196:197], v[176:177], v[160:161], v[162:163] op_sel_hi:[1,0,1]
	v_cndmask_b32_e64 v31, v31, v161, s[24:25]
	v_pk_fma_f32 v[198:199], v[178:179], v[160:161], v[164:165] op_sel_hi:[1,0,1]
	ds_read_b128 v[160:163], v28 offset:43008
	ds_read_b128 v[164:167], v28 offset:43264
	ds_read_b128 v[168:171], v28 offset:43520
	ds_read_b128 v[172:175], v28 offset:44032
	ds_read_b128 v[176:179], v28 offset:44288
	ds_read_b32 v202, v29 offset:43776
	s_waitcnt lgkmcnt(8)
	v_pk_mul_f32 v[190:191], v[190:191], v[198:199]
	v_pk_mul_f32 v[26:27], v[26:27], v[198:199]
	v_pk_fma_f32 v[188:189], v[188:189], v[196:197], v[190:191]
	v_pk_fma_f32 v[24:25], v[24:25], v[196:197], v[26:27]
	v_add_f32_e32 v206, v188, v189
	v_add_f32_e32 v24, v24, v25
	v_pk_mul_f32 v[26:27], v[180:181], v[196:197]
	s_waitcnt lgkmcnt(6)
	v_add_f32_dpp v25, v206, v206 quad_perm:[1,0,3,2] row_mask:0xf bank_mask:0xf bound_ctrl:1
	v_add_f32_dpp v24, v24, v24 quad_perm:[1,0,3,2] row_mask:0xf bank_mask:0xf bound_ctrl:1
	v_pk_mul_f32 v[180:181], v[182:183], v[198:199]
	v_add_f32_dpp v25, v25, v25 quad_perm:[2,3,0,1] row_mask:0xf bank_mask:0xf bound_ctrl:1
	v_add_f32_dpp v24, v24, v24 quad_perm:[2,3,0,1] row_mask:0xf bank_mask:0xf bound_ctrl:1
	v_pk_fma_f32 v[180:181], v[186:187], v[200:201], v[180:181] op_sel_hi:[1,0,1]
	v_add_f32_dpp v25, v25, v25 row_ror:4 row_mask:0xf bank_mask:0xf bound_ctrl:1
	v_add_f32_dpp v182, v24, v24 row_ror:4 row_mask:0xf bank_mask:0xf bound_ctrl:1
	v_pk_fma_f32 v[26:27], v[184:185], v[200:201], v[26:27] op_sel_hi:[1,0,1]
	v_add_f32_dpp v24, v25, v25 row_ror:8 row_mask:0xf bank_mask:0xf bound_ctrl:1
	v_add_f32_dpp v25, v182, v182 row_ror:8 row_mask:0xf bank_mask:0xf bound_ctrl:1
	v_pk_fma_f32 v[196:197], v[192:193], v[24:25], v[26:27] op_sel_hi:[1,0,1]
	v_cndmask_b32_e64 v31, v31, v25, s[26:27]
	v_pk_fma_f32 v[198:199], v[194:195], v[24:25], v[180:181] op_sel_hi:[1,0,1]
	ds_read_b128 v[24:27], v28 offset:44544
	ds_read_b128 v[180:183], v28 offset:44800
	ds_read_b128 v[184:187], v28 offset:45056
	ds_read_b128 v[188:191], v28 offset:45568
	ds_read_b128 v[192:195], v28 offset:45824
	ds_read_b32 v200, v29 offset:45312
	s_waitcnt lgkmcnt(8)
	v_pk_mul_f32 v[174:175], v[174:175], v[198:199]
	v_pk_mul_f32 v[34:35], v[34:35], v[198:199]
	v_pk_fma_f32 v[172:173], v[172:173], v[196:197], v[174:175]
	v_pk_fma_f32 v[32:33], v[32:33], v[196:197], v[34:35]
	v_add_f32_e32 v206, v172, v173
	v_add_f32_e32 v32, v32, v33
	v_pk_mul_f32 v[34:35], v[164:165], v[196:197]
	s_waitcnt lgkmcnt(6)
	v_add_f32_dpp v33, v206, v206 quad_perm:[1,0,3,2] row_mask:0xf bank_mask:0xf bound_ctrl:1
	v_add_f32_dpp v32, v32, v32 quad_perm:[1,0,3,2] row_mask:0xf bank_mask:0xf bound_ctrl:1
	v_pk_mul_f32 v[164:165], v[166:167], v[198:199]
	v_add_f32_dpp v33, v33, v33 quad_perm:[2,3,0,1] row_mask:0xf bank_mask:0xf bound_ctrl:1
	v_add_f32_dpp v32, v32, v32 quad_perm:[2,3,0,1] row_mask:0xf bank_mask:0xf bound_ctrl:1
	v_pk_fma_f32 v[164:165], v[170:171], v[202:203], v[164:165] op_sel_hi:[1,0,1]
	v_add_f32_dpp v33, v33, v33 row_ror:4 row_mask:0xf bank_mask:0xf bound_ctrl:1
	v_add_f32_dpp v166, v32, v32 row_ror:4 row_mask:0xf bank_mask:0xf bound_ctrl:1
	v_pk_fma_f32 v[34:35], v[168:169], v[202:203], v[34:35] op_sel_hi:[1,0,1]
	v_add_f32_dpp v32, v33, v33 row_ror:8 row_mask:0xf bank_mask:0xf bound_ctrl:1
	v_add_f32_dpp v33, v166, v166 row_ror:8 row_mask:0xf bank_mask:0xf bound_ctrl:1
	v_pk_fma_f32 v[196:197], v[176:177], v[32:33], v[34:35] op_sel_hi:[1,0,1]
	v_cndmask_b32_e64 v31, v31, v33, s[28:29]
	v_pk_fma_f32 v[198:199], v[178:179], v[32:33], v[164:165] op_sel_hi:[1,0,1]
	ds_read_b128 v[32:35], v28 offset:46080
	ds_read_b128 v[164:167], v28 offset:46336
	ds_read_b128 v[168:171], v28 offset:46592
	ds_read_b128 v[172:175], v28 offset:47104
	ds_read_b128 v[176:179], v28 offset:47360
	ds_read_b32 v202, v29 offset:46848
	s_waitcnt lgkmcnt(8)
	v_pk_mul_f32 v[190:191], v[190:191], v[198:199]
	v_pk_mul_f32 v[162:163], v[162:163], v[198:199]
	v_pk_fma_f32 v[188:189], v[188:189], v[196:197], v[190:191]
	v_pk_fma_f32 v[160:161], v[160:161], v[196:197], v[162:163]
	v_add_f32_e32 v206, v188, v189
	v_add_f32_e32 v160, v160, v161
	v_pk_mul_f32 v[162:163], v[180:181], v[196:197]
	s_waitcnt lgkmcnt(6)
; #define LAS __attribute__((address_space(3)))
; __device__ __forceinline__ void rwkv_scan_prompt(const Params& p, LAS unsigned char* lds, int bh, int rq) {
;     ...
;             for (int tk = 0; tk < TC; ++tk) {
;                 f32x4 nr4 = r4, nd4 = d4, nk4 = k4, na4 = a4, nb4 = b4; float nvv = vv;
;                 if (tk < TC - 1) {
;                     const LAS float* o = ob + (tk + 1) * 6 * 64;
;                     nr4 = *(const LAS f32x4*)(o + cg_ * 4); nd4 = *(const LAS f32x4*)(o + 64 + cg_ * 4); nk4 = *(const LAS f32x4*)(o + 128 + cg_ * 4);
;                     na4 = *(const LAS f32x4*)(o + 256 + cg_ * 4); nb4 = *(const LAS f32x4*)(o + 320 + cg_ * 4);
;                     nvv = o[192 + rq * 16 + rloc];
;                 }
;                 __builtin_amdgcn_sched_barrier(0);
;                 typedef float f32x2_ __attribute__((ext_vector_type(2)));
;                 f32x2_ ta = (f32x2_){S[0], S[1]} * (f32x2_){a4[0], a4[1]}; ta = (f32x2_){S[2], S[3]} * (f32x2_){a4[2], a4[3]} + ta;
;                 f32x2_ ty = (f32x2_){S[0], S[1]} * (f32x2_){rp[0], rp[1]}; ty = (f32x2_){S[2], S[3]} * (f32x2_){rp[2], rp[3]} + ty;
;                 const f32x4 T = S * d4 + vv * k4;
;                 float sa = ta[0] + ta[1];
;                 float yp = ty[0] + ty[1];
;                 sa = dpp_add<0xB1>(sa); yp = dpp_add<0xB1>(yp);
;                 sa = dpp_add<0x4E>(sa); yp = dpp_add<0x4E>(yp);
;                 sa = dpp_add<0x124>(sa); yp = dpp_add<0x124>(yp);
;                 sa = dpp_add<0x128>(sa); yp = dpp_add<0x128>(yp);
;                 if (tk > 0) yk[(tk - 1) >> 4] = (cg_ == ((tk - 1) & 15)) ? yp : yk[(tk - 1) >> 4];
;                 S = sa * b4 + T;
;                 rp = r4;
;                 r4 = nr4; d4 = nd4; k4 = nk4; a4 = na4; b4 = nb4; vv = nvv;
;             }
;             {
;                 float yp = S[0] * rp[0] + S[1] * rp[1] + S[2] * rp[2] + S[3] * rp[3];
;                 yp = row_sum16(yp);
;                 yk[(TC - 1) >> 4] = (cg_ == ((TC - 1) & 15)) ? yp : yk[(TC - 1) >> 4];
;             }
; #pragma unroll
;             for (int j = 0; j < TC / 16; ++j) yk[j] += RKB[buf * TC + j * 16 + cg_] * ob[(j * 16 + cg_) * 6 * 64 + 192 + rq * 16 + rloc];
; #pragma unroll
;             for (int j = 0; j < TC / 16; ++j) YRAW[(size_t)(rowbase + c * TC + j * 16 + cg_) * 512 + h * 64 + rq * 16 + rloc] = yk[j];
	v_add_f32_dpp v161, v206, v206 quad_perm:[1,0,3,2] row_mask:0xf bank_mask:0xf bound_ctrl:1
	v_add_f32_dpp v160, v160, v160 quad_perm:[1,0,3,2] row_mask:0xf bank_mask:0xf bound_ctrl:1
	v_pk_mul_f32 v[180:181], v[182:183], v[198:199]
	v_add_f32_dpp v161, v161, v161 quad_perm:[2,3,0,1] row_mask:0xf bank_mask:0xf bound_ctrl:1
	v_add_f32_dpp v160, v160, v160 quad_perm:[2,3,0,1] row_mask:0xf bank_mask:0xf bound_ctrl:1
	v_pk_fma_f32 v[180:181], v[186:187], v[200:201], v[180:181] op_sel_hi:[1,0,1]
	v_add_f32_dpp v161, v161, v161 row_ror:4 row_mask:0xf bank_mask:0xf bound_ctrl:1
	v_add_f32_dpp v182, v160, v160 row_ror:4 row_mask:0xf bank_mask:0xf bound_ctrl:1
	v_pk_fma_f32 v[162:163], v[184:185], v[200:201], v[162:163] op_sel_hi:[1,0,1]
	v_add_f32_dpp v160, v161, v161 row_ror:8 row_mask:0xf bank_mask:0xf bound_ctrl:1
	v_add_f32_dpp v161, v182, v182 row_ror:8 row_mask:0xf bank_mask:0xf bound_ctrl:1
	v_pk_fma_f32 v[196:197], v[192:193], v[160:161], v[162:163] op_sel_hi:[1,0,1]
	v_cndmask_b32_e64 v31, v31, v161, s[30:31]
	v_pk_fma_f32 v[198:199], v[194:195], v[160:161], v[180:181] op_sel_hi:[1,0,1]
	ds_read_b128 v[160:163], v28 offset:47616
	ds_read_b128 v[180:183], v28 offset:47872
	ds_read_b128 v[184:187], v28 offset:48128
	ds_read_b128 v[188:191], v28 offset:48640
	ds_read_b128 v[192:195], v28 offset:48896
	ds_read_b32 v28, v29 offset:48384
	s_waitcnt lgkmcnt(8)
	v_pk_mul_f32 v[174:175], v[174:175], v[198:199]
	v_pk_mul_f32 v[26:27], v[26:27], v[198:199]
	v_pk_fma_f32 v[172:173], v[172:173], v[196:197], v[174:175]
	v_pk_fma_f32 v[24:25], v[24:25], v[196:197], v[26:27]
	v_add_f32_e32 v29, v172, v173
	v_add_f32_e32 v24, v24, v25
	v_pk_mul_f32 v[26:27], v[164:165], v[196:197]
	v_add_f32_dpp v25, v29, v29 quad_perm:[1,0,3,2] row_mask:0xf bank_mask:0xf bound_ctrl:1
	v_add_f32_dpp v24, v24, v24 quad_perm:[1,0,3,2] row_mask:0xf bank_mask:0xf bound_ctrl:1
	v_pk_mul_f32 v[164:165], v[166:167], v[198:199]
	v_add_f32_dpp v25, v25, v25 quad_perm:[2,3,0,1] row_mask:0xf bank_mask:0xf bound_ctrl:1
	v_add_f32_dpp v24, v24, v24 quad_perm:[2,3,0,1] row_mask:0xf bank_mask:0xf bound_ctrl:1
	s_waitcnt lgkmcnt(6)
	v_pk_fma_f32 v[164:165], v[170:171], v[202:203], v[164:165] op_sel_hi:[1,0,1]
	v_add_f32_dpp v25, v25, v25 row_ror:4 row_mask:0xf bank_mask:0xf bound_ctrl:1
	v_add_f32_dpp v29, v24, v24 row_ror:4 row_mask:0xf bank_mask:0xf bound_ctrl:1
	v_pk_fma_f32 v[26:27], v[168:169], v[202:203], v[26:27] op_sel_hi:[1,0,1]
	v_add_f32_dpp v24, v25, v25 row_ror:8 row_mask:0xf bank_mask:0xf bound_ctrl:1
	v_add_f32_dpp v25, v29, v29 row_ror:8 row_mask:0xf bank_mask:0xf bound_ctrl:1
	v_cndmask_b32_e64 v29, v31, v25, s[34:35]
	v_pk_fma_f32 v[26:27], v[176:177], v[24:25], v[26:27] op_sel_hi:[1,0,1]
	v_pk_fma_f32 v[24:25], v[178:179], v[24:25], v[164:165] op_sel_hi:[1,0,1]
	s_waitcnt lgkmcnt(2)
	v_pk_mul_f32 v[164:165], v[190:191], v[24:25]
	v_pk_mul_f32 v[34:35], v[34:35], v[24:25]
	v_pk_fma_f32 v[164:165], v[188:189], v[26:27], v[164:165]
	v_pk_fma_f32 v[32:33], v[32:33], v[26:27], v[34:35]
	v_pk_mul_f32 v[26:27], v[180:181], v[26:27]
	v_pk_mul_f32 v[24:25], v[182:183], v[24:25]
	s_waitcnt lgkmcnt(0)
	v_pk_fma_f32 v[34:35], v[184:185], v[28:29], v[26:27] op_sel_hi:[1,0,1]
	v_add_f32_e32 v26, v164, v165
	v_add_f32_e32 v27, v32, v33
	v_pk_fma_f32 v[24:25], v[186:187], v[28:29], v[24:25] op_sel_hi:[1,0,1]
	v_add_f32_dpp v26, v26, v26 quad_perm:[1,0,3,2] row_mask:0xf bank_mask:0xf bound_ctrl:1
	v_add_f32_dpp v27, v27, v27 quad_perm:[1,0,3,2] row_mask:0xf bank_mask:0xf bound_ctrl:1
	s_lshl_b32 s79, s94, 2
	v_add_f32_dpp v26, v26, v26 quad_perm:[2,3,0,1] row_mask:0xf bank_mask:0xf bound_ctrl:1
	v_add_f32_dpp v27, v27, v27 quad_perm:[2,3,0,1] row_mask:0xf bank_mask:0xf bound_ctrl:1
	s_add_i32 s79, s79, s78
	v_add_f32_dpp v26, v26, v26 row_ror:4 row_mask:0xf bank_mask:0xf bound_ctrl:1
	v_add_f32_dpp v27, v27, v27 row_ror:4 row_mask:0xf bank_mask:0xf bound_ctrl:1
	v_add3_u32 v32, s79, v135, v84
	v_add_f32_dpp v28, v26, v26 row_ror:8 row_mask:0xf bank_mask:0xf bound_ctrl:1
	v_add_f32_dpp v26, v27, v27 row_ror:8 row_mask:0xf bank_mask:0xf bound_ctrl:1
	v_cndmask_b32_e64 v31, v29, v26, s[36:37]
	v_pk_fma_f32 v[26:27], v[194:195], v[28:29], v[24:25] op_sel_hi:[1,0,1]
	v_pk_fma_f32 v[24:25], v[192:193], v[28:29], v[34:35] op_sel_hi:[1,0,1]
	ds_read2st64_b32 v[32:33], v32 offset0:3 offset1:99
	v_mul_f32_e32 v28, v161, v25
	v_fmac_f32_e32 v28, v160, v24
	v_fmac_f32_e32 v28, v162, v26
	v_fmac_f32_e32 v28, v163, v27
	s_nop 1
	v_add_f32_dpp v34, v28, v28 quad_perm:[1,0,3,2] row_mask:0xf bank_mask:0xf bound_ctrl:1
	v_lshl_add_u32 v28, s95, 7, v126
	ds_read2_b32 v[28:29], v28 offset1:16
	v_add_f32_dpp v34, v34, v34 quad_perm:[2,3,0,1] row_mask:0xf bank_mask:0xf bound_ctrl:1
	s_waitcnt lgkmcnt(0)
	v_fmac_f32_e32 v30, v28, v32
	v_add_f32_dpp v34, v34, v34 row_ror:4 row_mask:0xf bank_mask:0xf bound_ctrl:1
	v_add_u32_e32 v28, s0, v159
	s_nop 0
	v_add_f32_dpp v34, v34, v34 row_ror:8 row_mask:0xf bank_mask:0xf bound_ctrl:1
	v_cndmask_b32_e64 v31, v31, v34, s[4:5]
	v_fmac_f32_e32 v31, v29, v33
	v_ashrrev_i32_e32 v29, 31, v28
	v_lshlrev_b64 v[32:33], 11, v[28:29]
	v_add_u32_e32 v28, 16, v28
	v_ashrrev_i32_e32 v29, 31, v28
	v_lshlrev_b64 v[28:29], 11, v[28:29]
	v_lshl_add_u64 v[32:33], v[88:89], 0, v[32:33]
	v_lshl_add_u64 v[28:29], v[88:89], 0, v[28:29]
	global_store_dword v[32:33], v30, off sc0 sc1
	global_store_dword v[28:29], v31, off sc0 sc1
